# xattn QK^T: fully unrolled software-pipelined stream (6-deep rotating K-fragment ring, 3-deep Q ring, SrcC=0 first step removes 127 zeroing moves)
# speedup vs baseline: 1.0114x; 1.0003x over previous
.LBB0_759:
	s_lshl_b32 s4, s53, 2
	s_or_b32 s54, s4, s52
	s_ashr_i32 s4, s54, 6
	s_ashr_i32 s5, s4, 31
	s_and_b32 s56, s52, 3
	s_lshl_b64 s[46:47], s[4:5], 20
	v_lshl_add_u64 v[0:1], v[150:151], 0, s[46:47]
	s_lshl_b32 s10, s56, 9
	v_lshl_add_u64 v[0:1], v[0:1], 0, s[10:11]
	v_readfirstlane_b32 s46, v223
	v_lshl_add_u64 v[160:161], v[0:1], 0, v[148:149]
	s_lshr_b32 s58, s46, 1
	s_lshl_b32 s59, s54, 6
	v_add_co_u32_e32 v168, vcc, s34, v160
	s_and_b32 s54, s58, 0x7fffffe0
	s_and_b32 s58, s59, 0xf00
	v_addc_co_u32_e32 v169, vcc, 0, v161, vcc
	s_lshl_b64 s[4:5], s[4:5], 12
	v_or_b32_e32 v66, s58, v176
	v_add_co_u32_e32 v164, vcc, s35, v160
	s_mov_b32 s55, s11
	v_or_b32_e32 v66, s4, v66
	v_mov_b32_e32 v67, s5
	v_addc_co_u32_e32 v165, vcc, 0, v161, vcc
	v_lshl_add_u64 v[66:67], v[66:67], 0, s[54:55]
	v_add_co_u32_e32 v166, vcc, s48, v160
	v_lshlrev_b64 v[68:69], 6, v[66:67]
	v_lshl_add_u64 v[0:1], v[160:161], 0, s[16:17]
	v_lshl_add_u64 v[46:47], v[160:161], 0, s[18:19]
	v_addc_co_u32_e32 v167, vcc, 0, v161, vcc
	v_lshlrev_b64 v[162:163], 11, v[66:67]
	v_lshl_add_u64 v[66:67], s[6:7], 0, v[68:69]
	global_load_dwordx4 v[2:5], v[160:161], off offset:48
	global_load_dwordx4 v[6:9], v[160:161], off offset:32
	global_load_dwordx4 v[10:13], v[160:161], off offset:16
	global_load_dwordx4 v[14:17], v[160:161], off
	global_load_dwordx4 v[18:21], v[0:1], off offset:32
	global_load_dwordx4 v[22:25], v[0:1], off offset:16
	global_load_dwordx4 v[26:29], v[168:169], off
	global_load_dwordx4 v[30:33], v[164:165], off
	global_load_dwordx4 v[34:37], v[46:47], off offset:48
	global_load_dwordx4 v[38:41], v[46:47], off offset:32
	global_load_dwordx4 v[42:45], v[0:1], off offset:48
	s_nop 0
	global_load_dwordx4 v[46:49], v[46:47], off offset:16
	v_lshl_add_u64 v[0:1], v[160:161], 0, s[36:37]
	global_load_dwordx4 v[50:53], v[166:167], off
	global_load_dwordx4 v[54:57], v[0:1], off offset:16
	global_load_dwordx4 v[58:61], v[0:1], off offset:32
	global_load_dwordx4 v[62:65], v[0:1], off offset:48
	s_mov_b32 s57, s11
	s_lshl_b32 s46, s56, 8
	s_lshl_b32 s56, s56, 4
	v_lshl_add_u64 v[68:69], s[8:9], 0, v[68:69]
	global_load_dwordx4 v[136:139], v[66:67], off offset:32
	global_load_dwordx4 v[140:143], v[66:67], off offset:16
	global_load_dwordx4 v[144:147], v[66:67], off
	v_lshl_add_u64 v[68:69], v[68:69], 0, s[56:57]
	global_load_dwordx4 v[132:135], v[66:67], off offset:48
	global_load_dwordx4 v[128:131], v[68:69], off
	v_mov_b32_e32 v0, 0
	v_or_b32_e32 v70, s10, v162
	v_mov_b32_e32 v71, v163
	s_mov_b32 s47, 0
	v_lshl_add_u64 v[170:171], v[152:153], 0, v[70:71]
	s_waitcnt vmcnt(17)
	ds_write_b128 v172, v[14:17]
	ds_write_b128 v172, v[10:13] offset:16
	ds_write_b128 v172, v[6:9] offset:32
	ds_write_b128 v172, v[2:5] offset:48
	s_waitcnt vmcnt(14)
	ds_write_b128 v172, v[26:29] offset:35840
	ds_write_b128 v172, v[22:25] offset:35856
	ds_write_b128 v172, v[18:21] offset:35872
	s_waitcnt vmcnt(10)
	ds_write_b128 v172, v[42:45] offset:35888
	ds_write_b128 v173, v[30:33]
	s_waitcnt vmcnt(9)
	ds_write_b128 v174, v[46:49]
	ds_write_b128 v175, v[38:41]
	ds_write_b128 v179, v[34:37]
	s_waitcnt vmcnt(8)
	ds_write_b128 v182, v[50:53]
	s_waitcnt vmcnt(7)
	ds_write_b128 v183, v[54:57]
	s_waitcnt vmcnt(6)
	ds_write_b128 v184, v[58:61]
	s_waitcnt vmcnt(5)
	ds_write_b128 v185, v[62:65]
	s_waitcnt lgkmcnt(0)
	s_barrier
.LBB0_760:
	v_add_u32_e32 v181, 0x11800, v211
	v_add_u32_e32 v220, 0x15e00, v211
	v_add_u32_e32 v221, 0x1a400, v211
	v_add_u32_e32 v222, 0x1ea00, v211
	global_load_dwordx4 v[212:215], v[170:171], off offset:-128
	global_load_dwordx4 v[216:219], v[170:171], off offset:-96
	global_load_dwordx4 v[248:251], v[170:171], off offset:-64
	ds_read_b128 v[224:227], v211
	ds_read_b128 v[228:231], v211 offset:17920
	ds_read_b128 v[232:235], v211 offset:35840
	ds_read_b128 v[236:239], v211 offset:53760
	ds_read_b128 v[240:243], v181
	ds_read_b128 v[244:247], v220
	s_waitcnt vmcnt(2) lgkmcnt(5)
	v_mfma_f32_32x32x16_bf16 v[112:127], v[224:227], v[212:215], 0
	ds_read_b128 v[224:227], v221
	s_waitcnt lgkmcnt(5)
	v_mfma_f32_32x32x16_bf16 v[96:111], v[228:231], v[212:215], 0
	ds_read_b128 v[228:231], v222
	s_waitcnt lgkmcnt(5)
	v_mfma_f32_32x32x16_bf16 v[80:95], v[232:235], v[212:215], 0
	ds_read_b128 v[232:235], v211 offset:32
	s_waitcnt lgkmcnt(5)
	v_mfma_f32_32x32x16_bf16 v[64:79], v[236:239], v[212:215], 0
	ds_read_b128 v[236:239], v211 offset:17952
	s_waitcnt lgkmcnt(5)
	v_mfma_f32_32x32x16_bf16 v[48:63], v[240:243], v[212:215], 0
	ds_read_b128 v[240:243], v211 offset:35872
	s_waitcnt lgkmcnt(5)
	v_mfma_f32_32x32x16_bf16 v[32:47], v[244:247], v[212:215], 0
	ds_read_b128 v[244:247], v211 offset:53792
	s_waitcnt lgkmcnt(5)
	v_mfma_f32_32x32x16_bf16 v[16:31], v[224:227], v[212:215], 0
	ds_read_b128 v[224:227], v181 offset:32
	s_waitcnt lgkmcnt(5)
	v_mfma_f32_32x32x16_bf16 v[0:15], v[228:231], v[212:215], 0
	ds_read_b128 v[228:231], v220 offset:32
	global_load_dwordx4 v[212:215], v[170:171], off offset:-32
	s_waitcnt vmcnt(2) lgkmcnt(5)
	v_mfma_f32_32x32x16_bf16 v[112:127], v[232:235], v[216:219], v[112:127]
	ds_read_b128 v[232:235], v221 offset:32
	s_waitcnt lgkmcnt(5)
	v_mfma_f32_32x32x16_bf16 v[96:111], v[236:239], v[216:219], v[96:111]
	ds_read_b128 v[236:239], v222 offset:32
	s_waitcnt lgkmcnt(5)
	v_mfma_f32_32x32x16_bf16 v[80:95], v[240:243], v[216:219], v[80:95]
	ds_read_b128 v[240:243], v211 offset:64
	s_waitcnt lgkmcnt(5)
	v_mfma_f32_32x32x16_bf16 v[64:79], v[244:247], v[216:219], v[64:79]
	ds_read_b128 v[244:247], v211 offset:17984
	s_waitcnt lgkmcnt(5)
	v_mfma_f32_32x32x16_bf16 v[48:63], v[224:227], v[216:219], v[48:63]
	ds_read_b128 v[224:227], v211 offset:35904
	s_waitcnt lgkmcnt(5)
	v_mfma_f32_32x32x16_bf16 v[32:47], v[228:231], v[216:219], v[32:47]
	ds_read_b128 v[228:231], v211 offset:53824
	s_waitcnt lgkmcnt(5)
	v_mfma_f32_32x32x16_bf16 v[16:31], v[232:235], v[216:219], v[16:31]
	ds_read_b128 v[232:235], v181 offset:64
	s_waitcnt lgkmcnt(5)
	v_mfma_f32_32x32x16_bf16 v[0:15], v[236:239], v[216:219], v[0:15]
	ds_read_b128 v[236:239], v220 offset:64
	global_load_dwordx4 v[216:219], v[170:171], off
	s_waitcnt vmcnt(2) lgkmcnt(5)
	v_mfma_f32_32x32x16_bf16 v[112:127], v[240:243], v[248:251], v[112:127]
	ds_read_b128 v[240:243], v221 offset:64
	s_waitcnt lgkmcnt(5)
	v_mfma_f32_32x32x16_bf16 v[96:111], v[244:247], v[248:251], v[96:111]
	ds_read_b128 v[244:247], v222 offset:64
	s_waitcnt lgkmcnt(5)
	v_mfma_f32_32x32x16_bf16 v[80:95], v[224:227], v[248:251], v[80:95]
	ds_read_b128 v[224:227], v211 offset:96
	s_waitcnt lgkmcnt(5)
	v_mfma_f32_32x32x16_bf16 v[64:79], v[228:231], v[248:251], v[64:79]
	ds_read_b128 v[228:231], v211 offset:18016
	s_waitcnt lgkmcnt(5)
	v_mfma_f32_32x32x16_bf16 v[48:63], v[232:235], v[248:251], v[48:63]
	ds_read_b128 v[232:235], v211 offset:35936
	s_waitcnt lgkmcnt(5)
	v_mfma_f32_32x32x16_bf16 v[32:47], v[236:239], v[248:251], v[32:47]
	ds_read_b128 v[236:239], v211 offset:53856
	s_waitcnt lgkmcnt(5)
	v_mfma_f32_32x32x16_bf16 v[16:31], v[240:243], v[248:251], v[16:31]
	ds_read_b128 v[240:243], v181 offset:96
	s_waitcnt lgkmcnt(5)
	v_mfma_f32_32x32x16_bf16 v[0:15], v[244:247], v[248:251], v[0:15]
	ds_read_b128 v[244:247], v220 offset:96
	global_load_dwordx4 v[248:251], v[170:171], off offset:32
	s_waitcnt vmcnt(2) lgkmcnt(5)
	v_mfma_f32_32x32x16_bf16 v[112:127], v[224:227], v[212:215], v[112:127]
	ds_read_b128 v[224:227], v221 offset:96
	s_waitcnt lgkmcnt(5)
	v_mfma_f32_32x32x16_bf16 v[96:111], v[228:231], v[212:215], v[96:111]
	ds_read_b128 v[228:231], v222 offset:96
	s_waitcnt lgkmcnt(5)
	v_mfma_f32_32x32x16_bf16 v[80:95], v[232:235], v[212:215], v[80:95]
	ds_read_b128 v[232:235], v211 offset:128
	s_waitcnt lgkmcnt(5)
	v_mfma_f32_32x32x16_bf16 v[64:79], v[236:239], v[212:215], v[64:79]
	ds_read_b128 v[236:239], v211 offset:18048
	s_waitcnt lgkmcnt(5)
	v_mfma_f32_32x32x16_bf16 v[48:63], v[240:243], v[212:215], v[48:63]
	ds_read_b128 v[240:243], v211 offset:35968
	s_waitcnt lgkmcnt(5)
	v_mfma_f32_32x32x16_bf16 v[32:47], v[244:247], v[212:215], v[32:47]
	ds_read_b128 v[244:247], v211 offset:53888
	s_waitcnt lgkmcnt(5)
	v_mfma_f32_32x32x16_bf16 v[16:31], v[224:227], v[212:215], v[16:31]
	ds_read_b128 v[224:227], v181 offset:128
	s_waitcnt lgkmcnt(5)
	v_mfma_f32_32x32x16_bf16 v[0:15], v[228:231], v[212:215], v[0:15]
	ds_read_b128 v[228:231], v220 offset:128
	global_load_dwordx4 v[212:215], v[170:171], off offset:64
	s_waitcnt vmcnt(2) lgkmcnt(5)
	v_mfma_f32_32x32x16_bf16 v[112:127], v[232:235], v[216:219], v[112:127]
	ds_read_b128 v[232:235], v221 offset:128
	s_waitcnt lgkmcnt(5)
	v_mfma_f32_32x32x16_bf16 v[96:111], v[236:239], v[216:219], v[96:111]
	ds_read_b128 v[236:239], v222 offset:128
	s_waitcnt lgkmcnt(5)
	v_mfma_f32_32x32x16_bf16 v[80:95], v[240:243], v[216:219], v[80:95]
	ds_read_b128 v[240:243], v211 offset:160
	s_waitcnt lgkmcnt(5)
	v_mfma_f32_32x32x16_bf16 v[64:79], v[244:247], v[216:219], v[64:79]
	ds_read_b128 v[244:247], v211 offset:18080
	s_waitcnt lgkmcnt(5)
	v_mfma_f32_32x32x16_bf16 v[48:63], v[224:227], v[216:219], v[48:63]
	ds_read_b128 v[224:227], v211 offset:36000
	s_waitcnt lgkmcnt(5)
	v_mfma_f32_32x32x16_bf16 v[32:47], v[228:231], v[216:219], v[32:47]
	ds_read_b128 v[228:231], v211 offset:53920
	s_waitcnt lgkmcnt(5)
	v_mfma_f32_32x32x16_bf16 v[16:31], v[232:235], v[216:219], v[16:31]
	ds_read_b128 v[232:235], v181 offset:160
	s_waitcnt lgkmcnt(5)
	v_mfma_f32_32x32x16_bf16 v[0:15], v[236:239], v[216:219], v[0:15]
	ds_read_b128 v[236:239], v220 offset:160
	global_load_dwordx4 v[216:219], v[170:171], off offset:96
	s_waitcnt vmcnt(2) lgkmcnt(5)
	v_mfma_f32_32x32x16_bf16 v[112:127], v[240:243], v[248:251], v[112:127]
	ds_read_b128 v[240:243], v221 offset:160
	s_waitcnt lgkmcnt(5)
	v_mfma_f32_32x32x16_bf16 v[96:111], v[244:247], v[248:251], v[96:111]
	ds_read_b128 v[244:247], v222 offset:160
	s_waitcnt lgkmcnt(5)
	v_mfma_f32_32x32x16_bf16 v[80:95], v[224:227], v[248:251], v[80:95]
	ds_read_b128 v[224:227], v211 offset:192
	s_waitcnt lgkmcnt(5)
	v_mfma_f32_32x32x16_bf16 v[64:79], v[228:231], v[248:251], v[64:79]
	ds_read_b128 v[228:231], v211 offset:18112
	s_waitcnt lgkmcnt(5)
	v_mfma_f32_32x32x16_bf16 v[48:63], v[232:235], v[248:251], v[48:63]
	ds_read_b128 v[232:235], v211 offset:36032
	s_waitcnt lgkmcnt(5)
	v_mfma_f32_32x32x16_bf16 v[32:47], v[236:239], v[248:251], v[32:47]
	ds_read_b128 v[236:239], v211 offset:53952
	s_waitcnt lgkmcnt(5)
	v_mfma_f32_32x32x16_bf16 v[16:31], v[240:243], v[248:251], v[16:31]
	ds_read_b128 v[240:243], v181 offset:192
	s_waitcnt lgkmcnt(5)
	v_mfma_f32_32x32x16_bf16 v[0:15], v[244:247], v[248:251], v[0:15]
	ds_read_b128 v[244:247], v220 offset:192
	global_load_dwordx4 v[248:251], v[170:171], off offset:128
	s_waitcnt vmcnt(2) lgkmcnt(5)
	v_mfma_f32_32x32x16_bf16 v[112:127], v[224:227], v[212:215], v[112:127]
	ds_read_b128 v[224:227], v221 offset:192
	s_waitcnt lgkmcnt(5)
	v_mfma_f32_32x32x16_bf16 v[96:111], v[228:231], v[212:215], v[96:111]
	ds_read_b128 v[228:231], v222 offset:192
	s_waitcnt lgkmcnt(5)
	v_mfma_f32_32x32x16_bf16 v[80:95], v[232:235], v[212:215], v[80:95]
	ds_read_b128 v[232:235], v211 offset:224
	s_waitcnt lgkmcnt(5)
	v_mfma_f32_32x32x16_bf16 v[64:79], v[236:239], v[212:215], v[64:79]
	ds_read_b128 v[236:239], v211 offset:18144
	s_waitcnt lgkmcnt(5)
	v_mfma_f32_32x32x16_bf16 v[48:63], v[240:243], v[212:215], v[48:63]
	ds_read_b128 v[240:243], v211 offset:36064
	s_waitcnt lgkmcnt(5)
	v_mfma_f32_32x32x16_bf16 v[32:47], v[244:247], v[212:215], v[32:47]
	ds_read_b128 v[244:247], v211 offset:53984
	s_waitcnt lgkmcnt(5)
	v_mfma_f32_32x32x16_bf16 v[16:31], v[224:227], v[212:215], v[16:31]
	ds_read_b128 v[224:227], v181 offset:224
	s_waitcnt lgkmcnt(5)
	v_mfma_f32_32x32x16_bf16 v[0:15], v[228:231], v[212:215], v[0:15]
	ds_read_b128 v[228:231], v220 offset:224
	global_load_dwordx4 v[212:215], v[170:171], off offset:160
	s_waitcnt vmcnt(2) lgkmcnt(5)
	v_mfma_f32_32x32x16_bf16 v[112:127], v[232:235], v[216:219], v[112:127]
	ds_read_b128 v[232:235], v221 offset:224
	s_waitcnt lgkmcnt(5)
	v_mfma_f32_32x32x16_bf16 v[96:111], v[236:239], v[216:219], v[96:111]
	ds_read_b128 v[236:239], v222 offset:224
	s_waitcnt lgkmcnt(5)
	v_mfma_f32_32x32x16_bf16 v[80:95], v[240:243], v[216:219], v[80:95]
	ds_read_b128 v[240:243], v211 offset:256
	s_waitcnt lgkmcnt(5)
	v_mfma_f32_32x32x16_bf16 v[64:79], v[244:247], v[216:219], v[64:79]
	ds_read_b128 v[244:247], v211 offset:18176
	s_waitcnt lgkmcnt(5)
	v_mfma_f32_32x32x16_bf16 v[48:63], v[224:227], v[216:219], v[48:63]
	ds_read_b128 v[224:227], v211 offset:36096
	s_waitcnt lgkmcnt(5)
	v_mfma_f32_32x32x16_bf16 v[32:47], v[228:231], v[216:219], v[32:47]
	ds_read_b128 v[228:231], v211 offset:54016
	s_waitcnt lgkmcnt(5)
	v_mfma_f32_32x32x16_bf16 v[16:31], v[232:235], v[216:219], v[16:31]
	ds_read_b128 v[232:235], v181 offset:256
	s_waitcnt lgkmcnt(5)
	v_mfma_f32_32x32x16_bf16 v[0:15], v[236:239], v[216:219], v[0:15]
	ds_read_b128 v[236:239], v220 offset:256
	global_load_dwordx4 v[216:219], v[170:171], off offset:192
	s_waitcnt vmcnt(2) lgkmcnt(5)
	v_mfma_f32_32x32x16_bf16 v[112:127], v[240:243], v[248:251], v[112:127]
	ds_read_b128 v[240:243], v221 offset:256
	s_waitcnt lgkmcnt(5)
	v_mfma_f32_32x32x16_bf16 v[96:111], v[244:247], v[248:251], v[96:111]
	ds_read_b128 v[244:247], v222 offset:256
	s_waitcnt lgkmcnt(5)
	v_mfma_f32_32x32x16_bf16 v[80:95], v[224:227], v[248:251], v[80:95]
	ds_read_b128 v[224:227], v211 offset:288
	s_waitcnt lgkmcnt(5)
	v_mfma_f32_32x32x16_bf16 v[64:79], v[228:231], v[248:251], v[64:79]
	ds_read_b128 v[228:231], v211 offset:18208
	s_waitcnt lgkmcnt(5)
	v_mfma_f32_32x32x16_bf16 v[48:63], v[232:235], v[248:251], v[48:63]
	ds_read_b128 v[232:235], v211 offset:36128
	s_waitcnt lgkmcnt(5)
	v_mfma_f32_32x32x16_bf16 v[32:47], v[236:239], v[248:251], v[32:47]
	ds_read_b128 v[236:239], v211 offset:54048
	s_waitcnt lgkmcnt(5)
	v_mfma_f32_32x32x16_bf16 v[16:31], v[240:243], v[248:251], v[16:31]
	ds_read_b128 v[240:243], v181 offset:288
	s_waitcnt lgkmcnt(5)
	v_mfma_f32_32x32x16_bf16 v[0:15], v[244:247], v[248:251], v[0:15]
	ds_read_b128 v[244:247], v220 offset:288
	global_load_dwordx4 v[248:251], v[170:171], off offset:224
	s_waitcnt vmcnt(2) lgkmcnt(5)
	v_mfma_f32_32x32x16_bf16 v[112:127], v[224:227], v[212:215], v[112:127]
	ds_read_b128 v[224:227], v221 offset:288
	s_waitcnt lgkmcnt(5)
	v_mfma_f32_32x32x16_bf16 v[96:111], v[228:231], v[212:215], v[96:111]
	ds_read_b128 v[228:231], v222 offset:288
	s_waitcnt lgkmcnt(5)
	v_mfma_f32_32x32x16_bf16 v[80:95], v[232:235], v[212:215], v[80:95]
	ds_read_b128 v[232:235], v211 offset:320
	s_waitcnt lgkmcnt(5)
	v_mfma_f32_32x32x16_bf16 v[64:79], v[236:239], v[212:215], v[64:79]
	ds_read_b128 v[236:239], v211 offset:18240
	s_waitcnt lgkmcnt(5)
	v_mfma_f32_32x32x16_bf16 v[48:63], v[240:243], v[212:215], v[48:63]
	ds_read_b128 v[240:243], v211 offset:36160
	s_waitcnt lgkmcnt(5)
	v_mfma_f32_32x32x16_bf16 v[32:47], v[244:247], v[212:215], v[32:47]
	ds_read_b128 v[244:247], v211 offset:54080
	s_waitcnt lgkmcnt(5)
	v_mfma_f32_32x32x16_bf16 v[16:31], v[224:227], v[212:215], v[16:31]
	ds_read_b128 v[224:227], v181 offset:320
	s_waitcnt lgkmcnt(5)
	v_mfma_f32_32x32x16_bf16 v[0:15], v[228:231], v[212:215], v[0:15]
	ds_read_b128 v[228:231], v220 offset:320
	global_load_dwordx4 v[212:215], v[170:171], off offset:256
	s_waitcnt vmcnt(2) lgkmcnt(5)
	v_mfma_f32_32x32x16_bf16 v[112:127], v[232:235], v[216:219], v[112:127]
	ds_read_b128 v[232:235], v221 offset:320
	s_waitcnt lgkmcnt(5)
	v_mfma_f32_32x32x16_bf16 v[96:111], v[236:239], v[216:219], v[96:111]
	ds_read_b128 v[236:239], v222 offset:320
	s_waitcnt lgkmcnt(5)
	v_mfma_f32_32x32x16_bf16 v[80:95], v[240:243], v[216:219], v[80:95]
	ds_read_b128 v[240:243], v211 offset:352
	s_waitcnt lgkmcnt(5)
	v_mfma_f32_32x32x16_bf16 v[64:79], v[244:247], v[216:219], v[64:79]
	ds_read_b128 v[244:247], v211 offset:18272
	s_waitcnt lgkmcnt(5)
	v_mfma_f32_32x32x16_bf16 v[48:63], v[224:227], v[216:219], v[48:63]
	ds_read_b128 v[224:227], v211 offset:36192
	s_waitcnt lgkmcnt(5)
	v_mfma_f32_32x32x16_bf16 v[32:47], v[228:231], v[216:219], v[32:47]
	ds_read_b128 v[228:231], v211 offset:54112
	s_waitcnt lgkmcnt(5)
	v_mfma_f32_32x32x16_bf16 v[16:31], v[232:235], v[216:219], v[16:31]
	ds_read_b128 v[232:235], v181 offset:352
	s_waitcnt lgkmcnt(5)
	v_mfma_f32_32x32x16_bf16 v[0:15], v[236:239], v[216:219], v[0:15]
	ds_read_b128 v[236:239], v220 offset:352
	global_load_dwordx4 v[216:219], v[170:171], off offset:288
	s_waitcnt vmcnt(2) lgkmcnt(5)
	v_mfma_f32_32x32x16_bf16 v[112:127], v[240:243], v[248:251], v[112:127]
	ds_read_b128 v[240:243], v221 offset:352
	s_waitcnt lgkmcnt(5)
	v_mfma_f32_32x32x16_bf16 v[96:111], v[244:247], v[248:251], v[96:111]
	ds_read_b128 v[244:247], v222 offset:352
	s_waitcnt lgkmcnt(5)
	v_mfma_f32_32x32x16_bf16 v[80:95], v[224:227], v[248:251], v[80:95]
	ds_read_b128 v[224:227], v211 offset:384
	s_waitcnt lgkmcnt(5)
	v_mfma_f32_32x32x16_bf16 v[64:79], v[228:231], v[248:251], v[64:79]
	ds_read_b128 v[228:231], v211 offset:18304
	s_waitcnt lgkmcnt(5)
	v_mfma_f32_32x32x16_bf16 v[48:63], v[232:235], v[248:251], v[48:63]
	ds_read_b128 v[232:235], v211 offset:36224
	s_waitcnt lgkmcnt(5)
	v_mfma_f32_32x32x16_bf16 v[32:47], v[236:239], v[248:251], v[32:47]
	ds_read_b128 v[236:239], v211 offset:54144
	s_waitcnt lgkmcnt(5)
	v_mfma_f32_32x32x16_bf16 v[16:31], v[240:243], v[248:251], v[16:31]
	ds_read_b128 v[240:243], v181 offset:384
	s_waitcnt lgkmcnt(5)
	v_mfma_f32_32x32x16_bf16 v[0:15], v[244:247], v[248:251], v[0:15]
	ds_read_b128 v[244:247], v220 offset:384
	global_load_dwordx4 v[248:251], v[170:171], off offset:320
	s_waitcnt vmcnt(2) lgkmcnt(5)
	v_mfma_f32_32x32x16_bf16 v[112:127], v[224:227], v[212:215], v[112:127]
	ds_read_b128 v[224:227], v221 offset:384
	s_waitcnt lgkmcnt(5)
	v_mfma_f32_32x32x16_bf16 v[96:111], v[228:231], v[212:215], v[96:111]
	ds_read_b128 v[228:231], v222 offset:384
	s_waitcnt lgkmcnt(5)
	v_mfma_f32_32x32x16_bf16 v[80:95], v[232:235], v[212:215], v[80:95]
	ds_read_b128 v[232:235], v211 offset:416
	s_waitcnt lgkmcnt(5)
	v_mfma_f32_32x32x16_bf16 v[64:79], v[236:239], v[212:215], v[64:79]
	ds_read_b128 v[236:239], v211 offset:18336
	s_waitcnt lgkmcnt(5)
	v_mfma_f32_32x32x16_bf16 v[48:63], v[240:243], v[212:215], v[48:63]
	ds_read_b128 v[240:243], v211 offset:36256
	s_waitcnt lgkmcnt(5)
	v_mfma_f32_32x32x16_bf16 v[32:47], v[244:247], v[212:215], v[32:47]
	ds_read_b128 v[244:247], v211 offset:54176
	s_waitcnt lgkmcnt(5)
	v_mfma_f32_32x32x16_bf16 v[16:31], v[224:227], v[212:215], v[16:31]
	ds_read_b128 v[224:227], v181 offset:416
	s_waitcnt lgkmcnt(5)
	v_mfma_f32_32x32x16_bf16 v[0:15], v[228:231], v[212:215], v[0:15]
	ds_read_b128 v[228:231], v220 offset:416
	global_load_dwordx4 v[212:215], v[170:171], off offset:352
	s_waitcnt vmcnt(2) lgkmcnt(5)
	v_mfma_f32_32x32x16_bf16 v[112:127], v[232:235], v[216:219], v[112:127]
	ds_read_b128 v[232:235], v221 offset:416
	s_waitcnt lgkmcnt(5)
	v_mfma_f32_32x32x16_bf16 v[96:111], v[236:239], v[216:219], v[96:111]
	ds_read_b128 v[236:239], v222 offset:416
	s_waitcnt lgkmcnt(5)
	v_mfma_f32_32x32x16_bf16 v[80:95], v[240:243], v[216:219], v[80:95]
	ds_read_b128 v[240:243], v211 offset:448
	s_waitcnt lgkmcnt(5)
	v_mfma_f32_32x32x16_bf16 v[64:79], v[244:247], v[216:219], v[64:79]
	ds_read_b128 v[244:247], v211 offset:18368
	s_waitcnt lgkmcnt(5)
	v_mfma_f32_32x32x16_bf16 v[48:63], v[224:227], v[216:219], v[48:63]
	ds_read_b128 v[224:227], v211 offset:36288
	s_waitcnt lgkmcnt(5)
	v_mfma_f32_32x32x16_bf16 v[32:47], v[228:231], v[216:219], v[32:47]
	ds_read_b128 v[228:231], v211 offset:54208
	s_waitcnt lgkmcnt(5)
	v_mfma_f32_32x32x16_bf16 v[16:31], v[232:235], v[216:219], v[16:31]
	ds_read_b128 v[232:235], v181 offset:448
	s_waitcnt lgkmcnt(5)
	v_mfma_f32_32x32x16_bf16 v[0:15], v[236:239], v[216:219], v[0:15]
	ds_read_b128 v[236:239], v220 offset:448
	s_waitcnt vmcnt(1) lgkmcnt(5)
	v_mfma_f32_32x32x16_bf16 v[112:127], v[240:243], v[248:251], v[112:127]
	ds_read_b128 v[240:243], v221 offset:448
	s_waitcnt lgkmcnt(5)
	v_mfma_f32_32x32x16_bf16 v[96:111], v[244:247], v[248:251], v[96:111]
	ds_read_b128 v[244:247], v222 offset:448
	s_waitcnt lgkmcnt(5)
	v_mfma_f32_32x32x16_bf16 v[80:95], v[224:227], v[248:251], v[80:95]
	ds_read_b128 v[224:227], v211 offset:480
	s_waitcnt lgkmcnt(5)
	v_mfma_f32_32x32x16_bf16 v[64:79], v[228:231], v[248:251], v[64:79]
	ds_read_b128 v[228:231], v211 offset:18400
	s_waitcnt lgkmcnt(5)
	v_mfma_f32_32x32x16_bf16 v[48:63], v[232:235], v[248:251], v[48:63]
	ds_read_b128 v[232:235], v211 offset:36320
	s_waitcnt lgkmcnt(5)
	v_mfma_f32_32x32x16_bf16 v[32:47], v[236:239], v[248:251], v[32:47]
	ds_read_b128 v[236:239], v211 offset:54240
	s_waitcnt lgkmcnt(5)
	v_mfma_f32_32x32x16_bf16 v[16:31], v[240:243], v[248:251], v[16:31]
	ds_read_b128 v[240:243], v181 offset:480
	s_waitcnt lgkmcnt(5)
	v_mfma_f32_32x32x16_bf16 v[0:15], v[244:247], v[248:251], v[0:15]
	ds_read_b128 v[244:247], v220 offset:480
	s_waitcnt vmcnt(0) lgkmcnt(5)
	v_mfma_f32_32x32x16_bf16 v[112:127], v[224:227], v[212:215], v[112:127]
	ds_read_b128 v[224:227], v221 offset:480
	s_waitcnt lgkmcnt(5)
	v_mfma_f32_32x32x16_bf16 v[96:111], v[228:231], v[212:215], v[96:111]
	ds_read_b128 v[228:231], v222 offset:480
	s_waitcnt lgkmcnt(5)
	v_mfma_f32_32x32x16_bf16 v[80:95], v[232:235], v[212:215], v[80:95]
	s_waitcnt lgkmcnt(4)
	v_mfma_f32_32x32x16_bf16 v[64:79], v[236:239], v[212:215], v[64:79]
	s_waitcnt lgkmcnt(3)
	v_mfma_f32_32x32x16_bf16 v[48:63], v[240:243], v[212:215], v[48:63]
	s_waitcnt lgkmcnt(2)
	v_mfma_f32_32x32x16_bf16 v[32:47], v[244:247], v[212:215], v[32:47]
	s_waitcnt lgkmcnt(1)
	v_mfma_f32_32x32x16_bf16 v[16:31], v[224:227], v[212:215], v[16:31]
	s_waitcnt lgkmcnt(0)
	v_mfma_f32_32x32x16_bf16 v[0:15], v[228:231], v[212:215], v[0:15]
	s_movk_i32 s47, 0x200
	v_mov_b32_e32 v170, v145
	v_mov_b32_e32 v171, v146
	v_mov_b32_e32 v145, v147
	v_mov_b32_e32 v146, v141
	v_mov_b32_e32 v147, v142
	v_mov_b32_e32 v141, v143
	v_pk_add_f32 v[144:145], v[170:171], v[144:145]
	v_pk_add_f32 v[140:141], v[146:147], v[140:141]
	v_pk_add_f32 v[144:145], v[144:145], v[144:145] op_sel:[0,1] op_sel_hi:[1,0]
	v_pk_add_f32 v[140:141], v[140:141], v[140:141] op_sel:[0,1] op_sel_hi:[1,0]
	v_add_f32_e32 v136, v136, v137
	v_add_f32_e32 v138, v138, v139
	v_mov_b32_e32 v145, v132
	v_mov_b32_e32 v141, v133
	v_mov_b32_e32 v137, v134
	v_mov_b32_e32 v139, v135
	v_pk_add_f32 v[132:133], v[144:145], v[140:141]
	v_pk_add_f32 v[134:135], v[136:137], v[138:139]
	s_lshl_b32 s10, s46, 1
	v_pk_add_f32 v[132:133], v[132:133], v[134:135]
	v_mov_b32_e32 v159, v149
	v_add_f32_e32 v132, v132, v133
	v_fmamk_f32 v132, v132, 0x3a800000, v180
	v_cmp_gt_f32_e32 vcc, s49, v132
	v_mul_f32_e32 v133, 0x4b800000, v132
	s_add_i32 s51, s51, 1
	v_cndmask_b32_e32 v132, v132, v133, vcc
	v_rsq_f32_e32 v132, v132
	s_nop 0
	v_mul_f32_e32 v133, 0x45800000, v132
	v_cndmask_b32_e32 v134, v132, v133, vcc
	v_mov_b32_e32 v132, v129
	v_mov_b32_e32 v133, v130
	v_mov_b32_e32 v129, v131
	v_pk_add_f32 v[128:129], v[132:133], v[128:129]
	v_and_b32_e32 v131, 64, v178
	v_add_f32_e32 v128, v128, v129
	v_mul_f32_e32 v129, v134, v134
	v_mul_f32_e32 v128, v128, v129
	v_fmamk_f32 v128, v128, 0x3b800000, v180
	v_cmp_gt_f32_e32 vcc, s49, v128
	v_mul_f32_e32 v129, 0x4b800000, v128
	v_add_u32_e32 v131, 64, v131
	v_cndmask_b32_e32 v128, v128, v129, vcc
	v_rsq_f32_e32 v128, v128
	s_nop 0
	v_mul_f32_e32 v129, 0x45800000, v128
	v_cndmask_b32_e32 v128, v128, v129, vcc
	v_max3_f32 v129, v112, s50, v113
	v_max3_f32 v129, v129, v114, v115
	v_max3_f32 v129, v129, v116, v117
	v_max3_f32 v129, v129, v118, v119
	v_max3_f32 v129, v129, v120, v121
	v_max3_f32 v129, v129, v122, v123
	v_max3_f32 v129, v129, v124, v125
	v_max3_f32 v129, v129, v126, v127
	v_max3_f32 v129, v129, v96, v97
	v_max3_f32 v129, v129, v98, v99
	v_max3_f32 v129, v129, v100, v101
	v_max3_f32 v129, v129, v102, v103
	v_max3_f32 v129, v129, v104, v105
	v_max3_f32 v129, v129, v106, v107
	v_max3_f32 v129, v129, v108, v109
	v_max3_f32 v129, v129, v110, v111
	v_max3_f32 v129, v129, v80, v81
	v_max3_f32 v129, v129, v82, v83
	v_max3_f32 v129, v129, v84, v85
	v_max3_f32 v129, v129, v86, v87
	v_max3_f32 v129, v129, v88, v89
	v_max3_f32 v129, v129, v90, v91
	v_max3_f32 v129, v129, v92, v93
	v_max3_f32 v129, v129, v94, v95
	v_max3_f32 v129, v129, v64, v65
	v_max3_f32 v129, v129, v66, v67
	v_max3_f32 v129, v129, v68, v69
	v_max3_f32 v129, v129, v70, v71
	v_max3_f32 v129, v129, v72, v73
	v_max3_f32 v129, v129, v74, v75
	v_max3_f32 v129, v129, v76, v77
	v_max3_f32 v129, v129, v78, v79
	v_max3_f32 v129, v129, v48, v49
	v_max3_f32 v129, v129, v50, v51
	v_max3_f32 v129, v129, v52, v53
	v_max3_f32 v129, v129, v54, v55
	v_max3_f32 v129, v129, v56, v57
	v_max3_f32 v129, v129, v58, v59
	v_max3_f32 v129, v129, v60, v61
	v_max3_f32 v129, v129, v62, v63
	v_max3_f32 v129, v129, v32, v33
	v_max3_f32 v129, v129, v34, v35
	v_max3_f32 v129, v129, v36, v37
	v_max3_f32 v129, v129, v38, v39
	v_max3_f32 v129, v129, v40, v41
	v_max3_f32 v129, v129, v42, v43
	v_max3_f32 v129, v129, v44, v45
	v_max3_f32 v129, v129, v46, v47
	v_max3_f32 v129, v129, v16, v17
	v_max3_f32 v129, v129, v18, v19
	v_max3_f32 v129, v129, v20, v21
	v_max3_f32 v129, v129, v22, v23
	v_max3_f32 v129, v129, v24, v25
	v_max3_f32 v129, v129, v26, v27
	v_max3_f32 v129, v129, v28, v29
	v_max3_f32 v129, v129, v30, v31
	v_max3_f32 v129, v129, v0, v1
	v_max3_f32 v129, v129, v2, v3
	v_max3_f32 v129, v129, v4, v5
	v_max3_f32 v129, v129, v6, v7
	v_max3_f32 v129, v129, v8, v9
	v_max3_f32 v129, v129, v10, v11
	v_mul_f32_e32 v128, v134, v128
	v_max3_f32 v129, v129, v12, v13
	v_max3_f32 v130, v129, v14, v15
	v_mul_f32_e32 v129, 0x3db8aa3b, v128
	v_xor_b32_e32 v128, 32, v178
	v_cmp_lt_i32_e32 vcc, v128, v131
	v_mul_f32_e32 v130, v129, v130
	s_nop 0
	v_cndmask_b32_e32 v128, v178, v128, vcc
	v_lshlrev_b32_e32 v128, 2, v128
	ds_bpermute_b32 v131, v128, v130
	s_waitcnt lgkmcnt(0)
	v_max_f32_e32 v131, v131, v131
	v_max_f32_e32 v130, v130, v131
	v_fma_f32 v112, v129, v112, -v130
	v_exp_f32_e32 v112, v112
	v_fma_f32 v113, v129, v113, -v130
	v_exp_f32_e32 v113, v113
	v_fma_f32 v114, v129, v114, -v130
	v_exp_f32_e32 v114, v114
	v_fma_f32 v115, v129, v115, -v130
	v_exp_f32_e32 v115, v115
	v_fma_f32 v116, v129, v116, -v130
	v_add_f32_e32 v131, 0, v112
	v_exp_f32_e32 v132, v116
	v_add_f32_e32 v131, v113, v131
	v_add_f32_e32 v131, v114, v131
	v_add_f32_e32 v131, v115, v131
	v_fma_f32 v117, v129, v117, -v130
	v_add_f32_e32 v116, v132, v131
	v_exp_f32_e32 v131, v117
	v_fma_f32 v117, v129, v118, -v130
	v_exp_f32_e32 v133, v117
	v_fma_f32 v117, v129, v119, -v130
	v_exp_f32_e32 v119, v117
	v_fma_f32 v117, v129, v120, -v130
	v_exp_f32_e32 v120, v117
	v_fma_f32 v117, v129, v121, -v130
	v_add_f32_e32 v116, v131, v116
	v_exp_f32_e32 v121, v117
	v_fma_f32 v117, v129, v122, -v130
	v_add_f32_e32 v116, v133, v116
	v_exp_f32_e32 v122, v117
	v_fma_f32 v117, v129, v123, -v130
	v_add_f32_e32 v116, v119, v116
	v_exp_f32_e32 v123, v117
	v_fma_f32 v117, v129, v124, -v130
	v_add_f32_e32 v116, v120, v116
	v_exp_f32_e32 v124, v117
	v_fma_f32 v117, v129, v125, -v130
	v_add_f32_e32 v116, v121, v116
	v_exp_f32_e32 v125, v117
	v_fma_f32 v117, v129, v126, -v130
	v_add_f32_e32 v116, v122, v116
	v_exp_f32_e32 v126, v117
	v_fma_f32 v117, v129, v127, -v130
	v_add_f32_e32 v116, v123, v116
	v_exp_f32_e32 v127, v117
	v_fma_f32 v96, v129, v96, -v130
	v_add_f32_e32 v116, v124, v116
	v_exp_f32_e32 v96, v96
	v_fma_f32 v97, v129, v97, -v130
	v_add_f32_e32 v116, v125, v116
	v_exp_f32_e32 v97, v97
	v_fma_f32 v98, v129, v98, -v130
	v_add_f32_e32 v116, v126, v116
	v_exp_f32_e32 v98, v98
	v_fma_f32 v99, v129, v99, -v130
	v_add_f32_e32 v134, v127, v116
	v_exp_f32_e32 v99, v99
	v_fma_f32 v100, v129, v100, -v130
	v_cvt_pk_bf16_f32 v116, v112, v113
	v_cvt_pk_bf16_f32 v112, v120, v121
	v_add_f32_e32 v120, v96, v134
	v_exp_f32_e32 v121, v100
	v_add_f32_e32 v120, v97, v120
	v_add_f32_e32 v120, v98, v120
	v_add_f32_e32 v120, v99, v120
	v_fma_f32 v101, v129, v101, -v130
	v_add_f32_e32 v100, v121, v120
	v_exp_f32_e32 v120, v101
	v_fma_f32 v101, v129, v102, -v130
	v_cvt_pk_bf16_f32 v113, v122, v123
	v_exp_f32_e32 v122, v101
	v_fma_f32 v101, v129, v103, -v130
	v_exp_f32_e32 v103, v101
	v_fma_f32 v101, v129, v104, -v130
	v_exp_f32_e32 v104, v101
	v_fma_f32 v101, v129, v105, -v130
	v_add_f32_e32 v100, v120, v100
	v_exp_f32_e32 v105, v101
	v_fma_f32 v101, v129, v106, -v130
	v_add_f32_e32 v100, v122, v100
	v_exp_f32_e32 v106, v101
	v_fma_f32 v101, v129, v107, -v130
	v_add_f32_e32 v100, v103, v100
	v_exp_f32_e32 v107, v101
	v_fma_f32 v101, v129, v108, -v130
	v_add_f32_e32 v100, v104, v100
	v_exp_f32_e32 v108, v101
	v_fma_f32 v101, v129, v109, -v130
	v_add_f32_e32 v100, v105, v100
	v_exp_f32_e32 v109, v101
	v_fma_f32 v101, v129, v110, -v130
	v_add_f32_e32 v100, v106, v100
	v_exp_f32_e32 v110, v101
	v_fma_f32 v101, v129, v111, -v130
	v_add_f32_e32 v100, v107, v100
	v_exp_f32_e32 v111, v101
	v_fma_f32 v80, v129, v80, -v130
	v_add_f32_e32 v100, v108, v100
	v_exp_f32_e32 v80, v80
	v_fma_f32 v81, v129, v81, -v130
	v_add_f32_e32 v100, v109, v100
	v_exp_f32_e32 v81, v81
	v_fma_f32 v82, v129, v82, -v130
	v_add_f32_e32 v100, v110, v100
	v_exp_f32_e32 v82, v82
	v_fma_f32 v83, v129, v83, -v130
	v_add_f32_e32 v123, v111, v100
	v_exp_f32_e32 v83, v83
	v_fma_f32 v84, v129, v84, -v130
	v_cvt_pk_bf16_f32 v100, v96, v97
	v_cvt_pk_bf16_f32 v96, v104, v105
	v_add_f32_e32 v104, v80, v123
	v_exp_f32_e32 v105, v84
	v_add_f32_e32 v104, v81, v104
	v_add_f32_e32 v104, v82, v104
	v_add_f32_e32 v104, v83, v104
	v_fma_f32 v85, v129, v85, -v130
	v_add_f32_e32 v84, v105, v104
	v_exp_f32_e32 v104, v85
	v_fma_f32 v85, v129, v86, -v130
	v_cvt_pk_bf16_f32 v97, v106, v107
	v_exp_f32_e32 v106, v85
	v_fma_f32 v85, v129, v87, -v130
	v_exp_f32_e32 v87, v85
	v_fma_f32 v85, v129, v88, -v130
	v_exp_f32_e32 v88, v85
	v_fma_f32 v85, v129, v89, -v130
	v_add_f32_e32 v84, v104, v84
	v_exp_f32_e32 v89, v85
	v_fma_f32 v85, v129, v90, -v130
	v_add_f32_e32 v84, v106, v84
	v_exp_f32_e32 v90, v85
	v_fma_f32 v85, v129, v91, -v130
	v_add_f32_e32 v84, v87, v84
	v_exp_f32_e32 v91, v85
	v_fma_f32 v85, v129, v92, -v130
	v_add_f32_e32 v84, v88, v84
	v_exp_f32_e32 v92, v85
	v_fma_f32 v85, v129, v93, -v130
	v_add_f32_e32 v84, v89, v84
	v_exp_f32_e32 v93, v85
	v_fma_f32 v85, v129, v94, -v130
	v_add_f32_e32 v84, v90, v84
	v_exp_f32_e32 v94, v85
	v_fma_f32 v85, v129, v95, -v130
	v_add_f32_e32 v84, v91, v84
	v_exp_f32_e32 v95, v85
	v_fma_f32 v64, v129, v64, -v130
	v_add_f32_e32 v84, v92, v84
	v_exp_f32_e32 v64, v64
	v_fma_f32 v65, v129, v65, -v130
	v_add_f32_e32 v84, v93, v84
	v_exp_f32_e32 v65, v65
	v_fma_f32 v66, v129, v66, -v130
	v_add_f32_e32 v84, v94, v84
	v_exp_f32_e32 v66, v66
	v_fma_f32 v67, v129, v67, -v130
	v_add_f32_e32 v107, v95, v84
	v_exp_f32_e32 v67, v67
	v_fma_f32 v68, v129, v68, -v130
	v_cvt_pk_bf16_f32 v84, v80, v81
	v_cvt_pk_bf16_f32 v80, v88, v89
	v_add_f32_e32 v88, v64, v107
	v_exp_f32_e32 v89, v68
	v_add_f32_e32 v88, v65, v88
	v_add_f32_e32 v88, v66, v88
	v_add_f32_e32 v88, v67, v88
	v_fma_f32 v69, v129, v69, -v130
	v_add_f32_e32 v68, v89, v88
	v_exp_f32_e32 v88, v69
	v_fma_f32 v69, v129, v70, -v130
	v_cvt_pk_bf16_f32 v81, v90, v91
	v_exp_f32_e32 v90, v69
	v_fma_f32 v69, v129, v71, -v130
	v_exp_f32_e32 v71, v69
	v_fma_f32 v69, v129, v72, -v130
	v_exp_f32_e32 v72, v69
	v_fma_f32 v69, v129, v73, -v130
	v_add_f32_e32 v68, v88, v68
	v_exp_f32_e32 v73, v69
	v_fma_f32 v69, v129, v74, -v130
	v_add_f32_e32 v68, v90, v68
	v_exp_f32_e32 v74, v69
	v_fma_f32 v69, v129, v75, -v130
	v_add_f32_e32 v68, v71, v68
	v_exp_f32_e32 v75, v69
	v_fma_f32 v69, v129, v76, -v130
	v_add_f32_e32 v68, v72, v68
	v_exp_f32_e32 v76, v69
	v_fma_f32 v69, v129, v77, -v130
	v_add_f32_e32 v68, v73, v68
	v_exp_f32_e32 v77, v69
	v_fma_f32 v69, v129, v78, -v130
	v_add_f32_e32 v68, v74, v68
	v_exp_f32_e32 v78, v69
	v_fma_f32 v69, v129, v79, -v130
	v_add_f32_e32 v68, v75, v68
	v_exp_f32_e32 v79, v69
	v_fma_f32 v48, v129, v48, -v130
	v_add_f32_e32 v68, v76, v68
	v_exp_f32_e32 v48, v48
	v_fma_f32 v49, v129, v49, -v130
	v_add_f32_e32 v68, v77, v68
	v_exp_f32_e32 v49, v49
	v_fma_f32 v50, v129, v50, -v130
	v_add_f32_e32 v68, v78, v68
	v_exp_f32_e32 v50, v50
	v_fma_f32 v51, v129, v51, -v130
	v_add_f32_e32 v91, v79, v68
	v_exp_f32_e32 v51, v51
	v_fma_f32 v52, v129, v52, -v130
	v_cvt_pk_bf16_f32 v68, v64, v65
	v_cvt_pk_bf16_f32 v64, v72, v73
	v_add_f32_e32 v72, v48, v91
	v_exp_f32_e32 v73, v52
	v_add_f32_e32 v72, v49, v72
	v_add_f32_e32 v72, v50, v72
	v_add_f32_e32 v72, v51, v72
	v_fma_f32 v53, v129, v53, -v130
	v_add_f32_e32 v52, v73, v72
	v_exp_f32_e32 v72, v53
	v_fma_f32 v53, v129, v54, -v130
	v_cvt_pk_bf16_f32 v65, v74, v75
	v_exp_f32_e32 v74, v53
	v_fma_f32 v53, v129, v55, -v130
	v_exp_f32_e32 v55, v53
	v_fma_f32 v53, v129, v56, -v130
	v_exp_f32_e32 v56, v53
	v_fma_f32 v53, v129, v57, -v130
	v_add_f32_e32 v52, v72, v52
	v_exp_f32_e32 v57, v53
	v_fma_f32 v53, v129, v58, -v130
	v_add_f32_e32 v52, v74, v52
	v_exp_f32_e32 v58, v53
	v_fma_f32 v53, v129, v59, -v130
	v_add_f32_e32 v52, v55, v52
	v_exp_f32_e32 v59, v53
	v_fma_f32 v53, v129, v60, -v130
	v_add_f32_e32 v52, v56, v52
	v_exp_f32_e32 v60, v53
	v_fma_f32 v53, v129, v61, -v130
	v_add_f32_e32 v52, v57, v52
	v_exp_f32_e32 v61, v53
	v_fma_f32 v53, v129, v62, -v130
	v_add_f32_e32 v52, v58, v52
	v_exp_f32_e32 v62, v53
	v_fma_f32 v53, v129, v63, -v130
	v_add_f32_e32 v52, v59, v52
	v_exp_f32_e32 v63, v53
	v_fma_f32 v32, v129, v32, -v130
	v_add_f32_e32 v52, v60, v52
	v_exp_f32_e32 v32, v32
	v_fma_f32 v33, v129, v33, -v130
	v_add_f32_e32 v52, v61, v52
	v_exp_f32_e32 v33, v33
	v_fma_f32 v34, v129, v34, -v130
	v_add_f32_e32 v52, v62, v52
	v_exp_f32_e32 v34, v34
	v_fma_f32 v35, v129, v35, -v130
	v_add_f32_e32 v75, v63, v52
	v_exp_f32_e32 v35, v35
	v_fma_f32 v36, v129, v36, -v130
	v_cvt_pk_bf16_f32 v52, v48, v49
	v_cvt_pk_bf16_f32 v48, v56, v57
	v_add_f32_e32 v56, v32, v75
	v_exp_f32_e32 v57, v36
	v_add_f32_e32 v56, v33, v56
	v_add_f32_e32 v56, v34, v56
	v_add_f32_e32 v56, v35, v56
	v_fma_f32 v37, v129, v37, -v130
	v_add_f32_e32 v36, v57, v56
	v_exp_f32_e32 v56, v37
	v_fma_f32 v37, v129, v38, -v130
	v_cvt_pk_bf16_f32 v49, v58, v59
	v_exp_f32_e32 v58, v37
	v_fma_f32 v37, v129, v39, -v130
	v_exp_f32_e32 v39, v37
	v_fma_f32 v37, v129, v40, -v130
	v_exp_f32_e32 v40, v37
	v_fma_f32 v37, v129, v41, -v130
	v_add_f32_e32 v36, v56, v36
	v_exp_f32_e32 v41, v37
	v_fma_f32 v37, v129, v42, -v130
	v_add_f32_e32 v36, v58, v36
	v_exp_f32_e32 v42, v37
	v_fma_f32 v37, v129, v43, -v130
	v_add_f32_e32 v36, v39, v36
	v_exp_f32_e32 v43, v37
	v_fma_f32 v37, v129, v44, -v130
	v_add_f32_e32 v36, v40, v36
	v_exp_f32_e32 v44, v37
	v_fma_f32 v37, v129, v45, -v130
	v_add_f32_e32 v36, v41, v36
	v_exp_f32_e32 v45, v37
	v_fma_f32 v37, v129, v46, -v130
	v_add_f32_e32 v36, v42, v36
	v_exp_f32_e32 v46, v37
	v_fma_f32 v37, v129, v47, -v130
	v_add_f32_e32 v36, v43, v36
	v_exp_f32_e32 v47, v37
	v_fma_f32 v16, v129, v16, -v130
	v_add_f32_e32 v36, v44, v36
	v_exp_f32_e32 v16, v16
	v_fma_f32 v17, v129, v17, -v130
	v_add_f32_e32 v36, v45, v36
	v_exp_f32_e32 v17, v17
	v_fma_f32 v18, v129, v18, -v130
	v_add_f32_e32 v36, v46, v36
	v_exp_f32_e32 v18, v18
	v_fma_f32 v19, v129, v19, -v130
	v_add_f32_e32 v59, v47, v36
	v_exp_f32_e32 v19, v19
	v_fma_f32 v20, v129, v20, -v130
	v_cvt_pk_bf16_f32 v36, v32, v33
	v_cvt_pk_bf16_f32 v32, v40, v41
	v_add_f32_e32 v40, v16, v59
	v_exp_f32_e32 v41, v20
	v_add_f32_e32 v40, v17, v40
	v_add_f32_e32 v40, v18, v40
	v_add_f32_e32 v40, v19, v40
	v_fma_f32 v21, v129, v21, -v130
	v_add_f32_e32 v20, v41, v40
	v_exp_f32_e32 v40, v21
	v_fma_f32 v21, v129, v22, -v130
	v_cvt_pk_bf16_f32 v33, v42, v43
	v_exp_f32_e32 v42, v21
	v_fma_f32 v21, v129, v23, -v130
	v_exp_f32_e32 v23, v21
	v_fma_f32 v21, v129, v24, -v130
	v_exp_f32_e32 v24, v21
	v_fma_f32 v21, v129, v25, -v130
	v_add_f32_e32 v20, v40, v20
	v_exp_f32_e32 v25, v21
	v_fma_f32 v21, v129, v26, -v130
	v_add_f32_e32 v20, v42, v20
	v_exp_f32_e32 v26, v21
	v_fma_f32 v21, v129, v27, -v130
	v_add_f32_e32 v20, v23, v20
	v_exp_f32_e32 v27, v21
	v_fma_f32 v21, v129, v28, -v130
	v_add_f32_e32 v20, v24, v20
	v_exp_f32_e32 v28, v21
	v_fma_f32 v21, v129, v29, -v130
	v_add_f32_e32 v20, v25, v20
	v_exp_f32_e32 v29, v21
	v_fma_f32 v21, v129, v30, -v130
	v_add_f32_e32 v20, v26, v20
	v_exp_f32_e32 v30, v21
	v_fma_f32 v21, v129, v31, -v130
	v_add_f32_e32 v20, v27, v20
	v_exp_f32_e32 v31, v21
	v_fma_f32 v0, v129, v0, -v130
	v_add_f32_e32 v20, v28, v20
	v_exp_f32_e32 v0, v0
	v_fma_f32 v1, v129, v1, -v130
	v_add_f32_e32 v20, v29, v20
	v_exp_f32_e32 v1, v1
	v_fma_f32 v2, v129, v2, -v130
	v_add_f32_e32 v20, v30, v20
	v_exp_f32_e32 v2, v2
	v_fma_f32 v3, v129, v3, -v130
	v_add_f32_e32 v43, v31, v20
	v_exp_f32_e32 v3, v3
	v_fma_f32 v4, v129, v4, -v130
	v_cvt_pk_bf16_f32 v20, v16, v17
	v_cvt_pk_bf16_f32 v16, v24, v25
	v_add_f32_e32 v24, v0, v43
	v_exp_f32_e32 v4, v4
	v_fma_f32 v5, v129, v5, -v130
	v_add_f32_e32 v24, v1, v24
	v_exp_f32_e32 v5, v5
	v_fma_f32 v6, v129, v6, -v130
	v_add_f32_e32 v24, v2, v24
	v_exp_f32_e32 v6, v6
	v_fma_f32 v7, v129, v7, -v130
	v_add_f32_e32 v24, v3, v24
	v_exp_f32_e32 v7, v7
	v_fma_f32 v8, v129, v8, -v130
	v_add_f32_e32 v24, v4, v24
	v_exp_f32_e32 v8, v8
	v_fma_f32 v9, v129, v9, -v130
	v_add_f32_e32 v24, v5, v24
	v_exp_f32_e32 v9, v9
	v_fma_f32 v10, v129, v10, -v130
	v_add_f32_e32 v24, v6, v24
	v_exp_f32_e32 v10, v10
	v_fma_f32 v11, v129, v11, -v130
	v_add_f32_e32 v24, v7, v24
	v_exp_f32_e32 v11, v11
	v_fma_f32 v12, v129, v12, -v130
	v_add_f32_e32 v24, v8, v24
	v_exp_f32_e32 v12, v12
	v_fma_f32 v13, v129, v13, -v130
	v_add_f32_e32 v24, v9, v24
	v_exp_f32_e32 v13, v13
	v_fma_f32 v14, v129, v14, -v130
	v_add_f32_e32 v24, v10, v24
	v_exp_f32_e32 v14, v14
	v_fma_f32 v15, v129, v15, -v130
	v_add_f32_e32 v24, v11, v24
	v_exp_f32_e32 v15, v15
	v_add_f32_e32 v24, v12, v24
	v_add_f32_e32 v24, v13, v24
	v_add_f32_e32 v24, v14, v24
	v_cvt_pk_bf16_f32 v22, v41, v40
	v_add_f32_e32 v40, v15, v24
	v_cvt_pk_bf16_f32 v21, v18, v19
	v_cvt_pk_bf16_f32 v18, v28, v29
	v_cvt_pk_bf16_f32 v28, v0, v1
	ds_bpermute_b32 v0, v128, v40
	v_cvt_pk_bf16_f32 v117, v114, v115
	v_cvt_pk_bf16_f32 v118, v132, v131
	v_cvt_pk_bf16_f32 v119, v133, v119
	v_cvt_pk_bf16_f32 v114, v124, v125
	v_cvt_pk_bf16_f32 v115, v126, v127
	v_cvt_pk_bf16_f32 v101, v98, v99
	v_cvt_pk_bf16_f32 v102, v121, v120
	v_cvt_pk_bf16_f32 v103, v122, v103
	v_cvt_pk_bf16_f32 v98, v108, v109
	v_cvt_pk_bf16_f32 v99, v110, v111
	v_cvt_pk_bf16_f32 v85, v82, v83
	v_cvt_pk_bf16_f32 v86, v105, v104
	v_cvt_pk_bf16_f32 v87, v106, v87
	v_cvt_pk_bf16_f32 v82, v92, v93
	v_cvt_pk_bf16_f32 v83, v94, v95
	v_cvt_pk_bf16_f32 v69, v66, v67
	v_cvt_pk_bf16_f32 v70, v89, v88
	v_cvt_pk_bf16_f32 v71, v90, v71
	v_cvt_pk_bf16_f32 v66, v76, v77
	v_cvt_pk_bf16_f32 v67, v78, v79
	v_cvt_pk_bf16_f32 v53, v50, v51
	v_cvt_pk_bf16_f32 v54, v73, v72
	v_cvt_pk_bf16_f32 v55, v74, v55
	v_cvt_pk_bf16_f32 v50, v60, v61
	v_cvt_pk_bf16_f32 v51, v62, v63
	v_cvt_pk_bf16_f32 v37, v34, v35
	v_cvt_pk_bf16_f32 v38, v57, v56
	v_cvt_pk_bf16_f32 v39, v58, v39
	v_cvt_pk_bf16_f32 v34, v44, v45
	v_cvt_pk_bf16_f32 v35, v46, v47
	v_cvt_pk_bf16_f32 v23, v42, v23
	v_cvt_pk_bf16_f32 v17, v26, v27
	v_cvt_pk_bf16_f32 v19, v30, v31
	v_cvt_pk_bf16_f32 v29, v2, v3
	v_cvt_pk_bf16_f32 v30, v4, v5
	v_cvt_pk_bf16_f32 v31, v6, v7
	v_cvt_pk_bf16_f32 v24, v8, v9
	v_cvt_pk_bf16_f32 v25, v10, v11
	v_cvt_pk_bf16_f32 v26, v12, v13
	v_cvt_pk_bf16_f32 v27, v14, v15
	v_lshl_add_u64 v[60:61], v[160:161], 0, s[38:39]
	s_waitcnt lgkmcnt(0)
	v_add_f32_e32 v72, v40, v0
	s_barrier
	global_load_dwordx4 v[0:3], v[160:161], off offset:2096
	global_load_dwordx4 v[4:7], v[160:161], off offset:2080
	global_load_dwordx4 v[8:11], v[160:161], off offset:2064
	global_load_dwordx4 v[12:15], v[160:161], off offset:2048
	global_load_dwordx4 v[40:43], v[168:169], off offset:2048
	global_load_dwordx4 v[44:47], v[60:61], off offset:48
	global_load_dwordx4 v[56:59], v[60:61], off offset:32
	s_nop 0
	global_load_dwordx4 v[60:63], v[60:61], off offset:16
	s_waitcnt vmcnt(4)
	ds_write_b128 v172, v[12:15]
	ds_write_b128 v172, v[8:11] offset:16
	ds_write_b128 v172, v[4:7] offset:32
	ds_write_b128 v172, v[0:3] offset:48
	s_waitcnt vmcnt(3)
	ds_write_b128 v172, v[40:43] offset:35840
	s_waitcnt vmcnt(0)
	ds_write_b128 v172, v[60:63] offset:35856
	ds_write_b128 v172, v[56:59] offset:35872
	ds_write_b128 v172, v[44:47] offset:35888
	v_lshl_add_u64 v[12:13], v[160:161], 0, s[40:41]
	v_lshl_add_u64 v[60:61], v[160:161], 0, s[44:45]
	global_load_dwordx4 v[0:3], v[164:165], off offset:2048
	global_load_dwordx4 v[4:7], v[12:13], off offset:48
	global_load_dwordx4 v[8:11], v[12:13], off offset:32
	s_nop 0
	global_load_dwordx4 v[12:15], v[12:13], off offset:16
	s_nop 0
	global_load_dwordx4 v[40:43], v[166:167], off offset:2048
	global_load_dwordx4 v[44:47], v[60:61], off offset:48
	global_load_dwordx4 v[56:59], v[60:61], off offset:32
	s_nop 0
	global_load_dwordx4 v[60:63], v[60:61], off offset:16
	s_waitcnt vmcnt(7)
	ds_write_b128 v173, v[0:3]
	s_waitcnt vmcnt(4)
	ds_write_b128 v174, v[12:15]
	ds_write_b128 v175, v[8:11]
	ds_write_b128 v179, v[4:7]
	s_waitcnt vmcnt(3)
	ds_write_b128 v182, v[40:43]
	s_waitcnt vmcnt(0)
	ds_write_b128 v183, v[60:63]
	ds_write_b128 v184, v[56:59]
	ds_write_b128 v185, v[44:47]
	v_div_scale_f32 v0, s[4:5], v72, v72, 1.0
	v_rcp_f32_e32 v1, v0
	s_waitcnt lgkmcnt(0)
	s_barrier
	v_fma_f32 v2, -v0, v1, 1.0
	v_fmac_f32_e32 v1, v2, v1
	v_div_scale_f32 v2, vcc, 1.0, v72, 1.0
	v_mul_f32_e32 v3, v2, v1
	v_fma_f32 v4, -v0, v3, v2
	v_fmac_f32_e32 v3, v4, v1
	v_fma_f32 v0, -v0, v3, v2
	v_div_fmas_f32 v0, v0, v1, v3
	v_div_fixup_f32 v44, v0, v72, 1.0
	v_lshl_add_u64 v[0:1], s[12:13], 0, v[162:163]
	v_lshl_add_u64 v[0:1], v[0:1], 0, s[10:11]
	v_lshl_add_u64 v[46:47], v[0:1], 0, v[158:159]
	v_mbcnt_lo_u32_b32 v40, -1, 0
	v_mbcnt_hi_u32_b32 v40, -1, v40
	v_and_b32_e32 v40, 32, v40
	v_lshrrev_b32_e32 v40, 2, v40
	v_mov_b32_e32 v41, 0
	v_lshl_add_u64 v[124:125], v[46:47], 0, v[40:41]
	ds_read_b64_tr_b16 v[56:57], v186
	ds_read_b64_tr_b16 v[58:59], v186 offset:4480
	ds_read_b64_tr_b16 v[60:61], v186 offset:8960
	ds_read_b64_tr_b16 v[62:63], v186 offset:13440
	ds_read_b64_tr_b16 v[88:89], v186 offset:17920
	ds_read_b64_tr_b16 v[90:91], v186 offset:22400
	ds_read_b64_tr_b16 v[92:93], v186 offset:26880
	ds_read_b64_tr_b16 v[94:95], v186 offset:31360
	ds_read_b64_tr_b16 v[104:105], v186 offset:35840
	ds_read_b64_tr_b16 v[106:107], v186 offset:40320
	ds_read_b64_tr_b16 v[108:109], v186 offset:44800
	ds_read_b64_tr_b16 v[110:111], v186 offset:49280
	ds_read_b64_tr_b16 v[120:121], v186 offset:53760
	ds_read_b64_tr_b16 v[122:123], v186 offset:58240
	s_mov_b64 s[4:5], 0
	s_waitcnt lgkmcnt(12)
	v_mfma_f32_32x32x16_bf16 v[0:15], v[56:59], v[116:119], 0
	v_add_u32_e32 v40, v187, v177
	ds_read_b64_tr_b16 v[56:57], v186 offset:62720
	ds_read_b64_tr_b16 v[58:59], v40
	s_waitcnt lgkmcnt(12)
	v_mfma_f32_32x32x16_bf16 v[0:15], v[60:63], v[112:115], v[0:15]
	v_add_u32_e32 v40, v188, v177
	v_add_u32_e32 v42, v189, v177
	ds_read_b64_tr_b16 v[60:61], v40
	ds_read_b64_tr_b16 v[62:63], v42
	s_waitcnt lgkmcnt(12)
	v_mfma_f32_32x32x16_bf16 v[0:15], v[88:91], v[100:103], v[0:15]
	v_add_u32_e32 v40, v190, v177
	v_add_u32_e32 v42, v191, v177
	ds_read_b64_tr_b16 v[88:89], v40
	ds_read_b64_tr_b16 v[90:91], v42
	s_waitcnt lgkmcnt(12)
	v_mfma_f32_32x32x16_bf16 v[0:15], v[92:95], v[96:99], v[0:15]
	v_add_u32_e32 v40, v192, v177
	v_add_u32_e32 v42, v193, v177
	ds_read_b64_tr_b16 v[92:93], v40
	ds_read_b64_tr_b16 v[94:95], v42
	s_waitcnt lgkmcnt(12)
	v_mfma_f32_32x32x16_bf16 v[0:15], v[104:107], v[84:87], v[0:15]
	v_add_u32_e32 v40, v194, v177
	v_add_u32_e32 v42, v195, v177
	ds_read_b64_tr_b16 v[104:105], v40
	ds_read_b64_tr_b16 v[106:107], v42
	s_waitcnt lgkmcnt(12)
	v_mfma_f32_32x32x16_bf16 v[0:15], v[108:111], v[80:83], v[0:15]
	v_add_u32_e32 v40, v196, v177
	v_add_u32_e32 v42, v197, v177
	ds_read_b64_tr_b16 v[108:109], v40
	ds_read_b64_tr_b16 v[110:111], v42
	s_waitcnt lgkmcnt(12)
	v_mfma_f32_32x32x16_bf16 v[0:15], v[120:123], v[68:71], v[0:15]
	v_add_u32_e32 v40, v198, v177
	v_add_u32_e32 v42, v199, v177
	ds_read_b64_tr_b16 v[120:121], v40
	ds_read_b64_tr_b16 v[122:123], v42
	s_waitcnt lgkmcnt(12)
	v_mfma_f32_32x32x16_bf16 v[0:15], v[56:59], v[64:67], v[0:15]
	v_add_u32_e32 v40, v200, v177
	v_add_u32_e32 v42, v201, v177
	ds_read_b64_tr_b16 v[56:57], v40
	ds_read_b64_tr_b16 v[58:59], v42
	s_waitcnt lgkmcnt(12)
	v_mfma_f32_32x32x16_bf16 v[0:15], v[60:63], v[52:55], v[0:15]
	v_add_u32_e32 v40, v202, v177
	v_add_u32_e32 v42, v203, v177
	ds_read_b64_tr_b16 v[60:61], v40
	ds_read_b64_tr_b16 v[62:63], v42
	s_waitcnt lgkmcnt(12)
	v_mfma_f32_32x32x16_bf16 v[0:15], v[88:91], v[48:51], v[0:15]
	ds_read_b64_tr_b16 v[88:89], v186 offset:64
	ds_read_b64_tr_b16 v[90:91], v186 offset:4544
	s_waitcnt lgkmcnt(12)
	v_mfma_f32_32x32x16_bf16 v[0:15], v[92:95], v[36:39], v[0:15]
	ds_read_b64_tr_b16 v[92:93], v186 offset:9024
	ds_read_b64_tr_b16 v[94:95], v186 offset:13504
	s_waitcnt lgkmcnt(12)
	v_mfma_f32_32x32x16_bf16 v[0:15], v[104:107], v[32:35], v[0:15]
	ds_read_b64_tr_b16 v[104:105], v186 offset:17984
	ds_read_b64_tr_b16 v[106:107], v186 offset:22464
	s_waitcnt lgkmcnt(12)
	v_mfma_f32_32x32x16_bf16 v[0:15], v[108:111], v[20:23], v[0:15]
	ds_read_b64_tr_b16 v[108:109], v186 offset:26944
	ds_read_b64_tr_b16 v[110:111], v186 offset:31424
	s_waitcnt lgkmcnt(12)
	v_mfma_f32_32x32x16_bf16 v[0:15], v[120:123], v[16:19], v[0:15]
	ds_read_b64_tr_b16 v[120:121], v186 offset:35904
	ds_read_b64_tr_b16 v[122:123], v186 offset:40384
	s_waitcnt lgkmcnt(12)
	v_mfma_f32_32x32x16_bf16 v[0:15], v[56:59], v[28:31], v[0:15]
	ds_read_b64_tr_b16 v[56:57], v186 offset:44864
	ds_read_b64_tr_b16 v[58:59], v186 offset:49344
	s_waitcnt lgkmcnt(12)
	v_mfma_f32_32x32x16_bf16 v[0:15], v[60:63], v[24:27], v[0:15]
	ds_read_b64_tr_b16 v[60:61], v186 offset:53824
	ds_read_b64_tr_b16 v[62:63], v186 offset:58304
	s_nop 11
	v_pk_mul_f32 v[0:1], v[0:1], v[44:45] op_sel_hi:[1,0]
	v_pk_mul_f32 v[2:3], v[2:3], v[44:45] op_sel_hi:[1,0]
	v_pk_mul_f32 v[4:5], v[4:5], v[44:45] op_sel_hi:[1,0]
	v_pk_mul_f32 v[6:7], v[6:7], v[44:45] op_sel_hi:[1,0]
	v_cvt_pk_bf16_f32 v0, v0, v1
	v_cvt_pk_bf16_f32 v1, v2, v3
	v_cvt_pk_bf16_f32 v2, v4, v5
	v_cvt_pk_bf16_f32 v3, v6, v7
	s_nop 1
	v_permlane32_swap_b32_e32 v0, v2
	v_permlane32_swap_b32_e32 v1, v3
	global_store_dwordx4 v[124:125], v[0:3], off
	v_pk_mul_f32 v[8:9], v[8:9], v[44:45] op_sel_hi:[1,0]
	v_pk_mul_f32 v[10:11], v[10:11], v[44:45] op_sel_hi:[1,0]
	v_pk_mul_f32 v[12:13], v[12:13], v[44:45] op_sel_hi:[1,0]
	v_pk_mul_f32 v[14:15], v[14:15], v[44:45] op_sel_hi:[1,0]
	v_cvt_pk_bf16_f32 v4, v8, v9
	v_cvt_pk_bf16_f32 v5, v10, v11
	v_cvt_pk_bf16_f32 v6, v12, v13
	v_cvt_pk_bf16_f32 v7, v14, v15
	s_nop 1
	v_permlane32_swap_b32_e32 v4, v6
	v_permlane32_swap_b32_e32 v5, v7
	global_store_dwordx4 v[124:125], v[4:7], off offset:32
	s_nop 1
	s_waitcnt lgkmcnt(12)
	v_mfma_f32_32x32x16_bf16 v[0:15], v[88:91], v[116:119], 0
	v_add_u32_e32 v40, v187, v204
	ds_read_b64_tr_b16 v[88:89], v186 offset:62784
	ds_read_b64_tr_b16 v[90:91], v40
	s_waitcnt lgkmcnt(12)
	v_mfma_f32_32x32x16_bf16 v[0:15], v[92:95], v[112:115], v[0:15]
	v_add_u32_e32 v40, v188, v204
	v_add_u32_e32 v42, v189, v204
	ds_read_b64_tr_b16 v[92:93], v40
	ds_read_b64_tr_b16 v[94:95], v42
	s_waitcnt lgkmcnt(12)
	v_mfma_f32_32x32x16_bf16 v[0:15], v[104:107], v[100:103], v[0:15]
	v_add_u32_e32 v40, v190, v204
	v_add_u32_e32 v42, v191, v204
	ds_read_b64_tr_b16 v[104:105], v40
	ds_read_b64_tr_b16 v[106:107], v42
	s_waitcnt lgkmcnt(12)
	v_mfma_f32_32x32x16_bf16 v[0:15], v[108:111], v[96:99], v[0:15]
	v_add_u32_e32 v40, v192, v204
	v_add_u32_e32 v42, v193, v204
	ds_read_b64_tr_b16 v[108:109], v40
	ds_read_b64_tr_b16 v[110:111], v42
	s_waitcnt lgkmcnt(12)
	v_mfma_f32_32x32x16_bf16 v[0:15], v[120:123], v[84:87], v[0:15]
	v_add_u32_e32 v40, v194, v204
	v_add_u32_e32 v42, v195, v204
	ds_read_b64_tr_b16 v[120:121], v40
	ds_read_b64_tr_b16 v[122:123], v42
	s_waitcnt lgkmcnt(12)
	v_mfma_f32_32x32x16_bf16 v[0:15], v[56:59], v[80:83], v[0:15]
	v_add_u32_e32 v40, v196, v204
	v_add_u32_e32 v42, v197, v204
	ds_read_b64_tr_b16 v[56:57], v40
	ds_read_b64_tr_b16 v[58:59], v42
	s_waitcnt lgkmcnt(12)
	v_mfma_f32_32x32x16_bf16 v[0:15], v[60:63], v[68:71], v[0:15]
	v_add_u32_e32 v40, v198, v204
	v_add_u32_e32 v42, v199, v204
	ds_read_b64_tr_b16 v[60:61], v40
	ds_read_b64_tr_b16 v[62:63], v42
	s_waitcnt lgkmcnt(12)
	v_mfma_f32_32x32x16_bf16 v[0:15], v[88:91], v[64:67], v[0:15]
	v_add_u32_e32 v40, v200, v204
	v_add_u32_e32 v42, v201, v204
	ds_read_b64_tr_b16 v[88:89], v40
	ds_read_b64_tr_b16 v[90:91], v42
	s_waitcnt lgkmcnt(12)
	v_mfma_f32_32x32x16_bf16 v[0:15], v[92:95], v[52:55], v[0:15]
	v_add_u32_e32 v40, v202, v204
	v_add_u32_e32 v42, v203, v204
	ds_read_b64_tr_b16 v[92:93], v40
	ds_read_b64_tr_b16 v[94:95], v42
	s_waitcnt lgkmcnt(12)
	v_mfma_f32_32x32x16_bf16 v[0:15], v[104:107], v[48:51], v[0:15]
	ds_read_b64_tr_b16 v[104:105], v186 offset:128
	ds_read_b64_tr_b16 v[106:107], v186 offset:4608
	s_waitcnt lgkmcnt(12)
	v_mfma_f32_32x32x16_bf16 v[0:15], v[108:111], v[36:39], v[0:15]
	ds_read_b64_tr_b16 v[108:109], v186 offset:9088
	ds_read_b64_tr_b16 v[110:111], v186 offset:13568
	s_waitcnt lgkmcnt(12)
	v_mfma_f32_32x32x16_bf16 v[0:15], v[120:123], v[32:35], v[0:15]
	ds_read_b64_tr_b16 v[120:121], v186 offset:18048
	ds_read_b64_tr_b16 v[122:123], v186 offset:22528
	s_waitcnt lgkmcnt(12)
	v_mfma_f32_32x32x16_bf16 v[0:15], v[56:59], v[20:23], v[0:15]
	ds_read_b64_tr_b16 v[56:57], v186 offset:27008
	ds_read_b64_tr_b16 v[58:59], v186 offset:31488
	s_waitcnt lgkmcnt(12)
	v_mfma_f32_32x32x16_bf16 v[0:15], v[60:63], v[16:19], v[0:15]
	ds_read_b64_tr_b16 v[60:61], v186 offset:35968
	ds_read_b64_tr_b16 v[62:63], v186 offset:40448
	s_waitcnt lgkmcnt(12)
	v_mfma_f32_32x32x16_bf16 v[0:15], v[88:91], v[28:31], v[0:15]
	ds_read_b64_tr_b16 v[88:89], v186 offset:44928
	ds_read_b64_tr_b16 v[90:91], v186 offset:49408
	s_waitcnt lgkmcnt(12)
	v_mfma_f32_32x32x16_bf16 v[0:15], v[92:95], v[24:27], v[0:15]
	ds_read_b64_tr_b16 v[92:93], v186 offset:53888
	ds_read_b64_tr_b16 v[94:95], v186 offset:58368
	s_nop 11
	v_pk_mul_f32 v[0:1], v[0:1], v[44:45] op_sel_hi:[1,0]
	v_pk_mul_f32 v[2:3], v[2:3], v[44:45] op_sel_hi:[1,0]
	v_pk_mul_f32 v[4:5], v[4:5], v[44:45] op_sel_hi:[1,0]
	v_pk_mul_f32 v[6:7], v[6:7], v[44:45] op_sel_hi:[1,0]
	v_cvt_pk_bf16_f32 v0, v0, v1
	v_cvt_pk_bf16_f32 v1, v2, v3
	v_cvt_pk_bf16_f32 v2, v4, v5
	v_cvt_pk_bf16_f32 v3, v6, v7
	s_nop 1
	v_permlane32_swap_b32_e32 v0, v2
	v_permlane32_swap_b32_e32 v1, v3
	global_store_dwordx4 v[124:125], v[0:3], off offset:64
	v_pk_mul_f32 v[8:9], v[8:9], v[44:45] op_sel_hi:[1,0]
	v_pk_mul_f32 v[10:11], v[10:11], v[44:45] op_sel_hi:[1,0]
	v_pk_mul_f32 v[12:13], v[12:13], v[44:45] op_sel_hi:[1,0]
	v_pk_mul_f32 v[14:15], v[14:15], v[44:45] op_sel_hi:[1,0]
	v_cvt_pk_bf16_f32 v4, v8, v9
	v_cvt_pk_bf16_f32 v5, v10, v11
	v_cvt_pk_bf16_f32 v6, v12, v13
	v_cvt_pk_bf16_f32 v7, v14, v15
	s_nop 1
	v_permlane32_swap_b32_e32 v4, v6
	v_permlane32_swap_b32_e32 v5, v7
	global_store_dwordx4 v[124:125], v[4:7], off offset:96
	s_nop 1
	s_waitcnt lgkmcnt(12)
	v_mfma_f32_32x32x16_bf16 v[0:15], v[104:107], v[116:119], 0
	v_add_u32_e32 v40, v187, v205
	ds_read_b64_tr_b16 v[104:105], v186 offset:62848
	ds_read_b64_tr_b16 v[106:107], v40
	s_waitcnt lgkmcnt(12)
	v_mfma_f32_32x32x16_bf16 v[0:15], v[108:111], v[112:115], v[0:15]
	v_add_u32_e32 v40, v188, v205
	v_add_u32_e32 v42, v189, v205
	ds_read_b64_tr_b16 v[108:109], v40
	ds_read_b64_tr_b16 v[110:111], v42
	s_waitcnt lgkmcnt(12)
	v_mfma_f32_32x32x16_bf16 v[0:15], v[120:123], v[100:103], v[0:15]
	v_add_u32_e32 v40, v190, v205
	v_add_u32_e32 v42, v191, v205
	ds_read_b64_tr_b16 v[120:121], v40
	ds_read_b64_tr_b16 v[122:123], v42
	s_waitcnt lgkmcnt(12)
	v_mfma_f32_32x32x16_bf16 v[0:15], v[56:59], v[96:99], v[0:15]
	v_add_u32_e32 v40, v192, v205
	v_add_u32_e32 v42, v193, v205
	ds_read_b64_tr_b16 v[56:57], v40
	ds_read_b64_tr_b16 v[58:59], v42
	s_waitcnt lgkmcnt(12)
	v_mfma_f32_32x32x16_bf16 v[0:15], v[60:63], v[84:87], v[0:15]
	v_add_u32_e32 v40, v194, v205
	v_add_u32_e32 v42, v195, v205
	ds_read_b64_tr_b16 v[60:61], v40
	ds_read_b64_tr_b16 v[62:63], v42
	s_waitcnt lgkmcnt(12)
	v_mfma_f32_32x32x16_bf16 v[0:15], v[88:91], v[80:83], v[0:15]
	v_add_u32_e32 v40, v196, v205
	v_add_u32_e32 v42, v197, v205
	ds_read_b64_tr_b16 v[88:89], v40
	ds_read_b64_tr_b16 v[90:91], v42
	s_waitcnt lgkmcnt(12)
	v_mfma_f32_32x32x16_bf16 v[0:15], v[92:95], v[68:71], v[0:15]
	v_add_u32_e32 v40, v198, v205
	v_add_u32_e32 v42, v199, v205
	ds_read_b64_tr_b16 v[92:93], v40
	ds_read_b64_tr_b16 v[94:95], v42
	s_waitcnt lgkmcnt(12)
	v_mfma_f32_32x32x16_bf16 v[0:15], v[104:107], v[64:67], v[0:15]
	v_add_u32_e32 v40, v200, v205
	v_add_u32_e32 v42, v201, v205
	ds_read_b64_tr_b16 v[104:105], v40
	ds_read_b64_tr_b16 v[106:107], v42
	s_waitcnt lgkmcnt(12)
	v_mfma_f32_32x32x16_bf16 v[0:15], v[108:111], v[52:55], v[0:15]
	v_add_u32_e32 v40, v202, v205
	v_add_u32_e32 v42, v203, v205
	ds_read_b64_tr_b16 v[108:109], v40
	ds_read_b64_tr_b16 v[110:111], v42
	s_waitcnt lgkmcnt(12)
	v_mfma_f32_32x32x16_bf16 v[0:15], v[120:123], v[48:51], v[0:15]
	ds_read_b64_tr_b16 v[120:121], v186 offset:192
	ds_read_b64_tr_b16 v[122:123], v186 offset:4672
	s_waitcnt lgkmcnt(12)
	v_mfma_f32_32x32x16_bf16 v[0:15], v[56:59], v[36:39], v[0:15]
	ds_read_b64_tr_b16 v[56:57], v186 offset:9152
	ds_read_b64_tr_b16 v[58:59], v186 offset:13632
	s_waitcnt lgkmcnt(12)
	v_mfma_f32_32x32x16_bf16 v[0:15], v[60:63], v[32:35], v[0:15]
	ds_read_b64_tr_b16 v[60:61], v186 offset:18112
	ds_read_b64_tr_b16 v[62:63], v186 offset:22592
	s_waitcnt lgkmcnt(12)
	v_mfma_f32_32x32x16_bf16 v[0:15], v[88:91], v[20:23], v[0:15]
	ds_read_b64_tr_b16 v[88:89], v186 offset:27072
	ds_read_b64_tr_b16 v[90:91], v186 offset:31552
	s_waitcnt lgkmcnt(12)
	v_mfma_f32_32x32x16_bf16 v[0:15], v[92:95], v[16:19], v[0:15]
	ds_read_b64_tr_b16 v[92:93], v186 offset:36032
	ds_read_b64_tr_b16 v[94:95], v186 offset:40512
	s_waitcnt lgkmcnt(12)
	v_mfma_f32_32x32x16_bf16 v[0:15], v[104:107], v[28:31], v[0:15]
	ds_read_b64_tr_b16 v[104:105], v186 offset:44992
	ds_read_b64_tr_b16 v[106:107], v186 offset:49472
	s_waitcnt lgkmcnt(12)
	v_mfma_f32_32x32x16_bf16 v[0:15], v[108:111], v[24:27], v[0:15]
	ds_read_b64_tr_b16 v[108:109], v186 offset:53952
	ds_read_b64_tr_b16 v[110:111], v186 offset:58432
	s_nop 11
	v_pk_mul_f32 v[0:1], v[0:1], v[44:45] op_sel_hi:[1,0]
	v_pk_mul_f32 v[2:3], v[2:3], v[44:45] op_sel_hi:[1,0]
	v_pk_mul_f32 v[4:5], v[4:5], v[44:45] op_sel_hi:[1,0]
	v_pk_mul_f32 v[6:7], v[6:7], v[44:45] op_sel_hi:[1,0]
	v_cvt_pk_bf16_f32 v0, v0, v1
	v_cvt_pk_bf16_f32 v1, v2, v3
	v_cvt_pk_bf16_f32 v2, v4, v5
	v_cvt_pk_bf16_f32 v3, v6, v7
	s_nop 1
	v_permlane32_swap_b32_e32 v0, v2
	v_permlane32_swap_b32_e32 v1, v3
	global_store_dwordx4 v[124:125], v[0:3], off offset:128
	v_pk_mul_f32 v[8:9], v[8:9], v[44:45] op_sel_hi:[1,0]
	v_pk_mul_f32 v[10:11], v[10:11], v[44:45] op_sel_hi:[1,0]
	v_pk_mul_f32 v[12:13], v[12:13], v[44:45] op_sel_hi:[1,0]
	v_pk_mul_f32 v[14:15], v[14:15], v[44:45] op_sel_hi:[1,0]
	v_cvt_pk_bf16_f32 v4, v8, v9
	v_cvt_pk_bf16_f32 v5, v10, v11
	v_cvt_pk_bf16_f32 v6, v12, v13
	v_cvt_pk_bf16_f32 v7, v14, v15
	s_nop 1
	v_permlane32_swap_b32_e32 v4, v6
	v_permlane32_swap_b32_e32 v5, v7
	global_store_dwordx4 v[124:125], v[4:7], off offset:160
	s_nop 1
	s_waitcnt lgkmcnt(12)
	v_mfma_f32_32x32x16_bf16 v[0:15], v[120:123], v[116:119], 0
	v_add_u32_e32 v40, v187, v206
	ds_read_b64_tr_b16 v[120:121], v186 offset:62912
	ds_read_b64_tr_b16 v[122:123], v40
	s_waitcnt lgkmcnt(12)
	v_mfma_f32_32x32x16_bf16 v[0:15], v[56:59], v[112:115], v[0:15]
	v_add_u32_e32 v40, v188, v206
	v_add_u32_e32 v42, v189, v206
	ds_read_b64_tr_b16 v[56:57], v40
	ds_read_b64_tr_b16 v[58:59], v42
	s_waitcnt lgkmcnt(12)
	v_mfma_f32_32x32x16_bf16 v[0:15], v[60:63], v[100:103], v[0:15]
	v_add_u32_e32 v40, v190, v206
	v_add_u32_e32 v42, v191, v206
	ds_read_b64_tr_b16 v[60:61], v40
	ds_read_b64_tr_b16 v[62:63], v42
	s_waitcnt lgkmcnt(12)
	v_mfma_f32_32x32x16_bf16 v[0:15], v[88:91], v[96:99], v[0:15]
	v_add_u32_e32 v40, v192, v206
	v_add_u32_e32 v42, v193, v206
	ds_read_b64_tr_b16 v[88:89], v40
	ds_read_b64_tr_b16 v[90:91], v42
	s_waitcnt lgkmcnt(12)
	v_mfma_f32_32x32x16_bf16 v[0:15], v[92:95], v[84:87], v[0:15]
	v_add_u32_e32 v40, v194, v206
	v_add_u32_e32 v42, v195, v206
	ds_read_b64_tr_b16 v[92:93], v40
	ds_read_b64_tr_b16 v[94:95], v42
	s_waitcnt lgkmcnt(12)
	v_mfma_f32_32x32x16_bf16 v[0:15], v[104:107], v[80:83], v[0:15]
	v_add_u32_e32 v40, v196, v206
	v_add_u32_e32 v42, v197, v206
	ds_read_b64_tr_b16 v[104:105], v40
	ds_read_b64_tr_b16 v[106:107], v42
	s_waitcnt lgkmcnt(12)
	v_mfma_f32_32x32x16_bf16 v[0:15], v[108:111], v[68:71], v[0:15]
	v_add_u32_e32 v40, v198, v206
	v_add_u32_e32 v42, v199, v206
	ds_read_b64_tr_b16 v[108:109], v40
	ds_read_b64_tr_b16 v[110:111], v42
	s_waitcnt lgkmcnt(12)
	v_mfma_f32_32x32x16_bf16 v[0:15], v[120:123], v[64:67], v[0:15]
	v_add_u32_e32 v40, v200, v206
	v_add_u32_e32 v42, v201, v206
	ds_read_b64_tr_b16 v[120:121], v40
	ds_read_b64_tr_b16 v[122:123], v42
	s_waitcnt lgkmcnt(12)
	v_mfma_f32_32x32x16_bf16 v[0:15], v[56:59], v[52:55], v[0:15]
	v_add_u32_e32 v40, v202, v206
	v_add_u32_e32 v42, v203, v206
	ds_read_b64_tr_b16 v[56:57], v40
	ds_read_b64_tr_b16 v[58:59], v42
	s_waitcnt lgkmcnt(12)
	v_mfma_f32_32x32x16_bf16 v[0:15], v[60:63], v[48:51], v[0:15]
	ds_read_b64_tr_b16 v[60:61], v186 offset:256
	ds_read_b64_tr_b16 v[62:63], v186 offset:4736
	s_waitcnt lgkmcnt(12)
	v_mfma_f32_32x32x16_bf16 v[0:15], v[88:91], v[36:39], v[0:15]
	ds_read_b64_tr_b16 v[88:89], v186 offset:9216
	ds_read_b64_tr_b16 v[90:91], v186 offset:13696
	s_waitcnt lgkmcnt(12)
	v_mfma_f32_32x32x16_bf16 v[0:15], v[92:95], v[32:35], v[0:15]
	ds_read_b64_tr_b16 v[92:93], v186 offset:18176
	ds_read_b64_tr_b16 v[94:95], v186 offset:22656
	s_waitcnt lgkmcnt(12)
	v_mfma_f32_32x32x16_bf16 v[0:15], v[104:107], v[20:23], v[0:15]
	ds_read_b64_tr_b16 v[104:105], v186 offset:27136
	ds_read_b64_tr_b16 v[106:107], v186 offset:31616
	s_waitcnt lgkmcnt(12)
	v_mfma_f32_32x32x16_bf16 v[0:15], v[108:111], v[16:19], v[0:15]
	ds_read_b64_tr_b16 v[108:109], v186 offset:36096
	ds_read_b64_tr_b16 v[110:111], v186 offset:40576
	s_waitcnt lgkmcnt(12)
	v_mfma_f32_32x32x16_bf16 v[0:15], v[120:123], v[28:31], v[0:15]
	ds_read_b64_tr_b16 v[120:121], v186 offset:45056
	ds_read_b64_tr_b16 v[122:123], v186 offset:49536
	s_waitcnt lgkmcnt(12)
	v_mfma_f32_32x32x16_bf16 v[0:15], v[56:59], v[24:27], v[0:15]
	ds_read_b64_tr_b16 v[56:57], v186 offset:54016
	ds_read_b64_tr_b16 v[58:59], v186 offset:58496
	s_nop 11
	v_pk_mul_f32 v[0:1], v[0:1], v[44:45] op_sel_hi:[1,0]
	v_pk_mul_f32 v[2:3], v[2:3], v[44:45] op_sel_hi:[1,0]
	v_pk_mul_f32 v[4:5], v[4:5], v[44:45] op_sel_hi:[1,0]
	v_pk_mul_f32 v[6:7], v[6:7], v[44:45] op_sel_hi:[1,0]
	v_cvt_pk_bf16_f32 v0, v0, v1
	v_cvt_pk_bf16_f32 v1, v2, v3
	v_cvt_pk_bf16_f32 v2, v4, v5
	v_cvt_pk_bf16_f32 v3, v6, v7
	s_nop 1
	v_permlane32_swap_b32_e32 v0, v2
	v_permlane32_swap_b32_e32 v1, v3
	global_store_dwordx4 v[124:125], v[0:3], off offset:192
	v_pk_mul_f32 v[8:9], v[8:9], v[44:45] op_sel_hi:[1,0]
	v_pk_mul_f32 v[10:11], v[10:11], v[44:45] op_sel_hi:[1,0]
	v_pk_mul_f32 v[12:13], v[12:13], v[44:45] op_sel_hi:[1,0]
	v_pk_mul_f32 v[14:15], v[14:15], v[44:45] op_sel_hi:[1,0]
	v_cvt_pk_bf16_f32 v4, v8, v9
	v_cvt_pk_bf16_f32 v5, v10, v11
	v_cvt_pk_bf16_f32 v6, v12, v13
	v_cvt_pk_bf16_f32 v7, v14, v15
	s_nop 1
	v_permlane32_swap_b32_e32 v4, v6
	v_permlane32_swap_b32_e32 v5, v7
	global_store_dwordx4 v[124:125], v[4:7], off offset:224
	s_nop 1
	s_waitcnt lgkmcnt(12)
	v_mfma_f32_32x32x16_bf16 v[0:15], v[60:63], v[116:119], 0
	v_add_u32_e32 v40, v187, v207
	ds_read_b64_tr_b16 v[60:61], v186 offset:62976
	ds_read_b64_tr_b16 v[62:63], v40
	s_waitcnt lgkmcnt(12)
	v_mfma_f32_32x32x16_bf16 v[0:15], v[88:91], v[112:115], v[0:15]
	v_add_u32_e32 v40, v188, v207
	v_add_u32_e32 v42, v189, v207
	ds_read_b64_tr_b16 v[88:89], v40
	ds_read_b64_tr_b16 v[90:91], v42
	s_waitcnt lgkmcnt(12)
	v_mfma_f32_32x32x16_bf16 v[0:15], v[92:95], v[100:103], v[0:15]
	v_add_u32_e32 v40, v190, v207
	v_add_u32_e32 v42, v191, v207
	ds_read_b64_tr_b16 v[92:93], v40
	ds_read_b64_tr_b16 v[94:95], v42
	s_waitcnt lgkmcnt(12)
	v_mfma_f32_32x32x16_bf16 v[0:15], v[104:107], v[96:99], v[0:15]
	v_add_u32_e32 v40, v192, v207
	v_add_u32_e32 v42, v193, v207
	ds_read_b64_tr_b16 v[104:105], v40
	ds_read_b64_tr_b16 v[106:107], v42
	s_waitcnt lgkmcnt(12)
	v_mfma_f32_32x32x16_bf16 v[0:15], v[108:111], v[84:87], v[0:15]
	v_add_u32_e32 v40, v194, v207
	v_add_u32_e32 v42, v195, v207
	ds_read_b64_tr_b16 v[108:109], v40
	ds_read_b64_tr_b16 v[110:111], v42
	s_waitcnt lgkmcnt(12)
	v_mfma_f32_32x32x16_bf16 v[0:15], v[120:123], v[80:83], v[0:15]
	v_add_u32_e32 v40, v196, v207
	v_add_u32_e32 v42, v197, v207
	ds_read_b64_tr_b16 v[120:121], v40
	ds_read_b64_tr_b16 v[122:123], v42
	s_waitcnt lgkmcnt(12)
	v_mfma_f32_32x32x16_bf16 v[0:15], v[56:59], v[68:71], v[0:15]
	v_add_u32_e32 v40, v198, v207
	v_add_u32_e32 v42, v199, v207
	ds_read_b64_tr_b16 v[56:57], v40
	ds_read_b64_tr_b16 v[58:59], v42
	s_waitcnt lgkmcnt(12)
	v_mfma_f32_32x32x16_bf16 v[0:15], v[60:63], v[64:67], v[0:15]
	v_add_u32_e32 v40, v200, v207
	v_add_u32_e32 v42, v201, v207
	ds_read_b64_tr_b16 v[60:61], v40
	ds_read_b64_tr_b16 v[62:63], v42
	s_waitcnt lgkmcnt(12)
	v_mfma_f32_32x32x16_bf16 v[0:15], v[88:91], v[52:55], v[0:15]
	v_add_u32_e32 v40, v202, v207
	v_add_u32_e32 v42, v203, v207
	ds_read_b64_tr_b16 v[88:89], v40
	ds_read_b64_tr_b16 v[90:91], v42
	s_waitcnt lgkmcnt(12)
	v_mfma_f32_32x32x16_bf16 v[0:15], v[92:95], v[48:51], v[0:15]
	ds_read_b64_tr_b16 v[92:93], v186 offset:320
	ds_read_b64_tr_b16 v[94:95], v186 offset:4800
	s_waitcnt lgkmcnt(12)
	v_mfma_f32_32x32x16_bf16 v[0:15], v[104:107], v[36:39], v[0:15]
	ds_read_b64_tr_b16 v[104:105], v186 offset:9280
	ds_read_b64_tr_b16 v[106:107], v186 offset:13760
	s_waitcnt lgkmcnt(12)
	v_mfma_f32_32x32x16_bf16 v[0:15], v[108:111], v[32:35], v[0:15]
	ds_read_b64_tr_b16 v[108:109], v186 offset:18240
	ds_read_b64_tr_b16 v[110:111], v186 offset:22720
	s_waitcnt lgkmcnt(12)
	v_mfma_f32_32x32x16_bf16 v[0:15], v[120:123], v[20:23], v[0:15]
	ds_read_b64_tr_b16 v[120:121], v186 offset:27200
	ds_read_b64_tr_b16 v[122:123], v186 offset:31680
	s_waitcnt lgkmcnt(12)
	v_mfma_f32_32x32x16_bf16 v[0:15], v[56:59], v[16:19], v[0:15]
	ds_read_b64_tr_b16 v[56:57], v186 offset:36160
	ds_read_b64_tr_b16 v[58:59], v186 offset:40640
	s_waitcnt lgkmcnt(12)
	v_mfma_f32_32x32x16_bf16 v[0:15], v[60:63], v[28:31], v[0:15]
	ds_read_b64_tr_b16 v[60:61], v186 offset:45120
	ds_read_b64_tr_b16 v[62:63], v186 offset:49600
	s_waitcnt lgkmcnt(12)
	v_mfma_f32_32x32x16_bf16 v[0:15], v[88:91], v[24:27], v[0:15]
	ds_read_b64_tr_b16 v[88:89], v186 offset:54080
	ds_read_b64_tr_b16 v[90:91], v186 offset:58560
	s_nop 11
	v_pk_mul_f32 v[0:1], v[0:1], v[44:45] op_sel_hi:[1,0]
	v_pk_mul_f32 v[2:3], v[2:3], v[44:45] op_sel_hi:[1,0]
	v_pk_mul_f32 v[4:5], v[4:5], v[44:45] op_sel_hi:[1,0]
	v_pk_mul_f32 v[6:7], v[6:7], v[44:45] op_sel_hi:[1,0]
	v_cvt_pk_bf16_f32 v0, v0, v1
	v_cvt_pk_bf16_f32 v1, v2, v3
	v_cvt_pk_bf16_f32 v2, v4, v5
	v_cvt_pk_bf16_f32 v3, v6, v7
	s_nop 1
	v_permlane32_swap_b32_e32 v0, v2
	v_permlane32_swap_b32_e32 v1, v3
	global_store_dwordx4 v[124:125], v[0:3], off offset:256
	v_pk_mul_f32 v[8:9], v[8:9], v[44:45] op_sel_hi:[1,0]
	v_pk_mul_f32 v[10:11], v[10:11], v[44:45] op_sel_hi:[1,0]
	v_pk_mul_f32 v[12:13], v[12:13], v[44:45] op_sel_hi:[1,0]
	v_pk_mul_f32 v[14:15], v[14:15], v[44:45] op_sel_hi:[1,0]
	v_cvt_pk_bf16_f32 v4, v8, v9
	v_cvt_pk_bf16_f32 v5, v10, v11
	v_cvt_pk_bf16_f32 v6, v12, v13
	v_cvt_pk_bf16_f32 v7, v14, v15
	s_nop 1
	v_permlane32_swap_b32_e32 v4, v6
	v_permlane32_swap_b32_e32 v5, v7
	global_store_dwordx4 v[124:125], v[4:7], off offset:288
	s_nop 1
	s_waitcnt lgkmcnt(12)
	v_mfma_f32_32x32x16_bf16 v[0:15], v[92:95], v[116:119], 0
	v_add_u32_e32 v40, v187, v208
	ds_read_b64_tr_b16 v[92:93], v186 offset:63040
	ds_read_b64_tr_b16 v[94:95], v40
	s_waitcnt lgkmcnt(12)
	v_mfma_f32_32x32x16_bf16 v[0:15], v[104:107], v[112:115], v[0:15]
	v_add_u32_e32 v40, v188, v208
	v_add_u32_e32 v42, v189, v208
	ds_read_b64_tr_b16 v[104:105], v40
	ds_read_b64_tr_b16 v[106:107], v42
	s_waitcnt lgkmcnt(12)
	v_mfma_f32_32x32x16_bf16 v[0:15], v[108:111], v[100:103], v[0:15]
	v_add_u32_e32 v40, v190, v208
	v_add_u32_e32 v42, v191, v208
	ds_read_b64_tr_b16 v[108:109], v40
	ds_read_b64_tr_b16 v[110:111], v42
	s_waitcnt lgkmcnt(12)
	v_mfma_f32_32x32x16_bf16 v[0:15], v[120:123], v[96:99], v[0:15]
	v_add_u32_e32 v40, v192, v208
	v_add_u32_e32 v42, v193, v208
	ds_read_b64_tr_b16 v[120:121], v40
	ds_read_b64_tr_b16 v[122:123], v42
	s_waitcnt lgkmcnt(12)
	v_mfma_f32_32x32x16_bf16 v[0:15], v[56:59], v[84:87], v[0:15]
	v_add_u32_e32 v40, v194, v208
	v_add_u32_e32 v42, v195, v208
	ds_read_b64_tr_b16 v[56:57], v40
	ds_read_b64_tr_b16 v[58:59], v42
	s_waitcnt lgkmcnt(12)
	v_mfma_f32_32x32x16_bf16 v[0:15], v[60:63], v[80:83], v[0:15]
	v_add_u32_e32 v40, v196, v208
	v_add_u32_e32 v42, v197, v208
	ds_read_b64_tr_b16 v[60:61], v40
	ds_read_b64_tr_b16 v[62:63], v42
	s_waitcnt lgkmcnt(12)
	v_mfma_f32_32x32x16_bf16 v[0:15], v[88:91], v[68:71], v[0:15]
	v_add_u32_e32 v40, v198, v208
	v_add_u32_e32 v42, v199, v208
	ds_read_b64_tr_b16 v[88:89], v40
	ds_read_b64_tr_b16 v[90:91], v42
	s_waitcnt lgkmcnt(12)
	v_mfma_f32_32x32x16_bf16 v[0:15], v[92:95], v[64:67], v[0:15]
	v_add_u32_e32 v40, v200, v208
	v_add_u32_e32 v42, v201, v208
	ds_read_b64_tr_b16 v[92:93], v40
	ds_read_b64_tr_b16 v[94:95], v42
	s_waitcnt lgkmcnt(12)
	v_mfma_f32_32x32x16_bf16 v[0:15], v[104:107], v[52:55], v[0:15]
	v_add_u32_e32 v40, v202, v208
	v_add_u32_e32 v42, v203, v208
	ds_read_b64_tr_b16 v[104:105], v40
	ds_read_b64_tr_b16 v[106:107], v42
	s_waitcnt lgkmcnt(12)
	v_mfma_f32_32x32x16_bf16 v[0:15], v[108:111], v[48:51], v[0:15]
	ds_read_b64_tr_b16 v[108:109], v186 offset:384
	ds_read_b64_tr_b16 v[110:111], v186 offset:4864
	s_waitcnt lgkmcnt(12)
	v_mfma_f32_32x32x16_bf16 v[0:15], v[120:123], v[36:39], v[0:15]
	ds_read_b64_tr_b16 v[120:121], v186 offset:9344
	ds_read_b64_tr_b16 v[122:123], v186 offset:13824
	s_waitcnt lgkmcnt(12)
	v_mfma_f32_32x32x16_bf16 v[0:15], v[56:59], v[32:35], v[0:15]
	ds_read_b64_tr_b16 v[56:57], v186 offset:18304
	ds_read_b64_tr_b16 v[58:59], v186 offset:22784
	s_waitcnt lgkmcnt(12)
	v_mfma_f32_32x32x16_bf16 v[0:15], v[60:63], v[20:23], v[0:15]
	ds_read_b64_tr_b16 v[60:61], v186 offset:27264
	ds_read_b64_tr_b16 v[62:63], v186 offset:31744
	s_waitcnt lgkmcnt(12)
	v_mfma_f32_32x32x16_bf16 v[0:15], v[88:91], v[16:19], v[0:15]
	ds_read_b64_tr_b16 v[88:89], v186 offset:36224
	ds_read_b64_tr_b16 v[90:91], v186 offset:40704
	s_waitcnt lgkmcnt(12)
	v_mfma_f32_32x32x16_bf16 v[0:15], v[92:95], v[28:31], v[0:15]
	ds_read_b64_tr_b16 v[92:93], v186 offset:45184
	ds_read_b64_tr_b16 v[94:95], v186 offset:49664
	s_waitcnt lgkmcnt(12)
	v_mfma_f32_32x32x16_bf16 v[0:15], v[104:107], v[24:27], v[0:15]
	ds_read_b64_tr_b16 v[104:105], v186 offset:54144
	ds_read_b64_tr_b16 v[106:107], v186 offset:58624
	s_nop 11
	v_pk_mul_f32 v[0:1], v[0:1], v[44:45] op_sel_hi:[1,0]
	v_pk_mul_f32 v[2:3], v[2:3], v[44:45] op_sel_hi:[1,0]
	v_pk_mul_f32 v[4:5], v[4:5], v[44:45] op_sel_hi:[1,0]
	v_pk_mul_f32 v[6:7], v[6:7], v[44:45] op_sel_hi:[1,0]
	v_cvt_pk_bf16_f32 v0, v0, v1
	v_cvt_pk_bf16_f32 v1, v2, v3
	v_cvt_pk_bf16_f32 v2, v4, v5
	v_cvt_pk_bf16_f32 v3, v6, v7
	s_nop 1
	v_permlane32_swap_b32_e32 v0, v2
	v_permlane32_swap_b32_e32 v1, v3
	global_store_dwordx4 v[124:125], v[0:3], off offset:320
	v_pk_mul_f32 v[8:9], v[8:9], v[44:45] op_sel_hi:[1,0]
	v_pk_mul_f32 v[10:11], v[10:11], v[44:45] op_sel_hi:[1,0]
	v_pk_mul_f32 v[12:13], v[12:13], v[44:45] op_sel_hi:[1,0]
	v_pk_mul_f32 v[14:15], v[14:15], v[44:45] op_sel_hi:[1,0]
	v_cvt_pk_bf16_f32 v4, v8, v9
	v_cvt_pk_bf16_f32 v5, v10, v11
	v_cvt_pk_bf16_f32 v6, v12, v13
	v_cvt_pk_bf16_f32 v7, v14, v15
	s_nop 1
	v_permlane32_swap_b32_e32 v4, v6
	v_permlane32_swap_b32_e32 v5, v7
	global_store_dwordx4 v[124:125], v[4:7], off offset:352
	s_nop 1
	s_waitcnt lgkmcnt(12)
	v_mfma_f32_32x32x16_bf16 v[0:15], v[108:111], v[116:119], 0
	v_add_u32_e32 v40, v187, v209
	ds_read_b64_tr_b16 v[108:109], v186 offset:63104
	ds_read_b64_tr_b16 v[110:111], v40
	s_waitcnt lgkmcnt(12)
	v_mfma_f32_32x32x16_bf16 v[0:15], v[120:123], v[112:115], v[0:15]
	v_add_u32_e32 v40, v188, v209
	v_add_u32_e32 v42, v189, v209
	ds_read_b64_tr_b16 v[120:121], v40
	ds_read_b64_tr_b16 v[122:123], v42
	s_waitcnt lgkmcnt(12)
	v_mfma_f32_32x32x16_bf16 v[0:15], v[56:59], v[100:103], v[0:15]
	v_add_u32_e32 v40, v190, v209
	v_add_u32_e32 v42, v191, v209
	ds_read_b64_tr_b16 v[56:57], v40
	ds_read_b64_tr_b16 v[58:59], v42
	s_waitcnt lgkmcnt(12)
	v_mfma_f32_32x32x16_bf16 v[0:15], v[60:63], v[96:99], v[0:15]
	v_add_u32_e32 v40, v192, v209
	v_add_u32_e32 v42, v193, v209
	ds_read_b64_tr_b16 v[60:61], v40
	ds_read_b64_tr_b16 v[62:63], v42
	s_waitcnt lgkmcnt(12)
	v_mfma_f32_32x32x16_bf16 v[0:15], v[88:91], v[84:87], v[0:15]
	v_add_u32_e32 v40, v194, v209
	v_add_u32_e32 v42, v195, v209
	ds_read_b64_tr_b16 v[88:89], v40
	ds_read_b64_tr_b16 v[90:91], v42
	s_waitcnt lgkmcnt(12)
	v_mfma_f32_32x32x16_bf16 v[0:15], v[92:95], v[80:83], v[0:15]
	v_add_u32_e32 v40, v196, v209
	v_add_u32_e32 v42, v197, v209
	ds_read_b64_tr_b16 v[92:93], v40
	ds_read_b64_tr_b16 v[94:95], v42
	s_waitcnt lgkmcnt(12)
	v_mfma_f32_32x32x16_bf16 v[0:15], v[104:107], v[68:71], v[0:15]
	v_add_u32_e32 v40, v198, v209
	v_add_u32_e32 v42, v199, v209
	ds_read_b64_tr_b16 v[104:105], v40
	ds_read_b64_tr_b16 v[106:107], v42
	s_waitcnt lgkmcnt(12)
	v_mfma_f32_32x32x16_bf16 v[0:15], v[108:111], v[64:67], v[0:15]
	v_add_u32_e32 v40, v200, v209
	v_add_u32_e32 v42, v201, v209
	ds_read_b64_tr_b16 v[108:109], v40
	ds_read_b64_tr_b16 v[110:111], v42
	s_waitcnt lgkmcnt(12)
	v_mfma_f32_32x32x16_bf16 v[0:15], v[120:123], v[52:55], v[0:15]
	v_add_u32_e32 v40, v202, v209
	v_add_u32_e32 v42, v203, v209
	ds_read_b64_tr_b16 v[120:121], v40
	ds_read_b64_tr_b16 v[122:123], v42
	s_waitcnt lgkmcnt(12)
	v_mfma_f32_32x32x16_bf16 v[0:15], v[56:59], v[48:51], v[0:15]
	ds_read_b64_tr_b16 v[56:57], v186 offset:448
	ds_read_b64_tr_b16 v[58:59], v186 offset:4928
	s_waitcnt lgkmcnt(12)
	v_mfma_f32_32x32x16_bf16 v[0:15], v[60:63], v[36:39], v[0:15]
	ds_read_b64_tr_b16 v[60:61], v186 offset:9408
	ds_read_b64_tr_b16 v[62:63], v186 offset:13888
	s_waitcnt lgkmcnt(12)
	v_mfma_f32_32x32x16_bf16 v[0:15], v[88:91], v[32:35], v[0:15]
	ds_read_b64_tr_b16 v[88:89], v186 offset:18368
	ds_read_b64_tr_b16 v[90:91], v186 offset:22848
	s_waitcnt lgkmcnt(12)
	v_mfma_f32_32x32x16_bf16 v[0:15], v[92:95], v[20:23], v[0:15]
	ds_read_b64_tr_b16 v[92:93], v186 offset:27328
	ds_read_b64_tr_b16 v[94:95], v186 offset:31808
	s_waitcnt lgkmcnt(12)
	v_mfma_f32_32x32x16_bf16 v[0:15], v[104:107], v[16:19], v[0:15]
	ds_read_b64_tr_b16 v[104:105], v186 offset:36288
	ds_read_b64_tr_b16 v[106:107], v186 offset:40768
	s_waitcnt lgkmcnt(12)
	v_mfma_f32_32x32x16_bf16 v[0:15], v[108:111], v[28:31], v[0:15]
	ds_read_b64_tr_b16 v[108:109], v186 offset:45248
	ds_read_b64_tr_b16 v[110:111], v186 offset:49728
	s_waitcnt lgkmcnt(12)
	v_mfma_f32_32x32x16_bf16 v[0:15], v[120:123], v[24:27], v[0:15]
	ds_read_b64_tr_b16 v[120:121], v186 offset:54208
	ds_read_b64_tr_b16 v[122:123], v186 offset:58688
	s_nop 11
	v_pk_mul_f32 v[0:1], v[0:1], v[44:45] op_sel_hi:[1,0]
	v_pk_mul_f32 v[2:3], v[2:3], v[44:45] op_sel_hi:[1,0]
	v_pk_mul_f32 v[4:5], v[4:5], v[44:45] op_sel_hi:[1,0]
	v_pk_mul_f32 v[6:7], v[6:7], v[44:45] op_sel_hi:[1,0]
	v_cvt_pk_bf16_f32 v0, v0, v1
	v_cvt_pk_bf16_f32 v1, v2, v3
	v_cvt_pk_bf16_f32 v2, v4, v5
	v_cvt_pk_bf16_f32 v3, v6, v7
	s_nop 1
	v_permlane32_swap_b32_e32 v0, v2
	v_permlane32_swap_b32_e32 v1, v3
	global_store_dwordx4 v[124:125], v[0:3], off offset:384
	v_pk_mul_f32 v[8:9], v[8:9], v[44:45] op_sel_hi:[1,0]
	v_pk_mul_f32 v[10:11], v[10:11], v[44:45] op_sel_hi:[1,0]
	v_pk_mul_f32 v[12:13], v[12:13], v[44:45] op_sel_hi:[1,0]
	v_pk_mul_f32 v[14:15], v[14:15], v[44:45] op_sel_hi:[1,0]
	v_cvt_pk_bf16_f32 v4, v8, v9
	v_cvt_pk_bf16_f32 v5, v10, v11
	v_cvt_pk_bf16_f32 v6, v12, v13
	v_cvt_pk_bf16_f32 v7, v14, v15
	s_nop 1
	v_permlane32_swap_b32_e32 v4, v6
	v_permlane32_swap_b32_e32 v5, v7
	global_store_dwordx4 v[124:125], v[4:7], off offset:416
	s_nop 1
	s_waitcnt lgkmcnt(12)
	v_mfma_f32_32x32x16_bf16 v[0:15], v[56:59], v[116:119], 0
	v_add_u32_e32 v40, v187, v210
	ds_read_b64_tr_b16 v[56:57], v186 offset:63168
	ds_read_b64_tr_b16 v[58:59], v40
	s_waitcnt lgkmcnt(12)
	v_mfma_f32_32x32x16_bf16 v[0:15], v[60:63], v[112:115], v[0:15]
	v_add_u32_e32 v40, v188, v210
	v_add_u32_e32 v42, v189, v210
	ds_read_b64_tr_b16 v[60:61], v40
	ds_read_b64_tr_b16 v[62:63], v42
	s_waitcnt lgkmcnt(12)
	v_mfma_f32_32x32x16_bf16 v[0:15], v[88:91], v[100:103], v[0:15]
	v_add_u32_e32 v40, v190, v210
	v_add_u32_e32 v42, v191, v210
	ds_read_b64_tr_b16 v[88:89], v40
	ds_read_b64_tr_b16 v[90:91], v42
	s_waitcnt lgkmcnt(12)
	v_mfma_f32_32x32x16_bf16 v[0:15], v[92:95], v[96:99], v[0:15]
	v_add_u32_e32 v40, v192, v210
	v_add_u32_e32 v42, v193, v210
	ds_read_b64_tr_b16 v[92:93], v40
	ds_read_b64_tr_b16 v[94:95], v42
	s_waitcnt lgkmcnt(12)
	v_mfma_f32_32x32x16_bf16 v[0:15], v[104:107], v[84:87], v[0:15]
	v_add_u32_e32 v40, v194, v210
	v_add_u32_e32 v42, v195, v210
	ds_read_b64_tr_b16 v[104:105], v40
	ds_read_b64_tr_b16 v[106:107], v42
	s_waitcnt lgkmcnt(12)
	v_mfma_f32_32x32x16_bf16 v[0:15], v[108:111], v[80:83], v[0:15]
	v_add_u32_e32 v40, v196, v210
	v_add_u32_e32 v42, v197, v210
	ds_read_b64_tr_b16 v[108:109], v40
	ds_read_b64_tr_b16 v[110:111], v42
	s_waitcnt lgkmcnt(12)
	v_mfma_f32_32x32x16_bf16 v[0:15], v[120:123], v[68:71], v[0:15]
	v_add_u32_e32 v40, v198, v210
	v_add_u32_e32 v42, v199, v210
	ds_read_b64_tr_b16 v[120:121], v40
	ds_read_b64_tr_b16 v[122:123], v42
	s_waitcnt lgkmcnt(12)
	v_mfma_f32_32x32x16_bf16 v[0:15], v[56:59], v[64:67], v[0:15]
	v_add_u32_e32 v40, v200, v210
	v_add_u32_e32 v42, v201, v210
	ds_read_b64_tr_b16 v[56:57], v40
	ds_read_b64_tr_b16 v[58:59], v42
	s_waitcnt lgkmcnt(12)
	v_mfma_f32_32x32x16_bf16 v[0:15], v[60:63], v[52:55], v[0:15]
	v_add_u32_e32 v40, v202, v210
	v_add_u32_e32 v42, v203, v210
	ds_read_b64_tr_b16 v[60:61], v40
	ds_read_b64_tr_b16 v[62:63], v42
	s_waitcnt lgkmcnt(12)
	v_mfma_f32_32x32x16_bf16 v[0:15], v[88:91], v[48:51], v[0:15]
	s_waitcnt lgkmcnt(10)
	v_mfma_f32_32x32x16_bf16 v[0:15], v[92:95], v[36:39], v[0:15]
	s_waitcnt lgkmcnt(8)
	v_mfma_f32_32x32x16_bf16 v[0:15], v[104:107], v[32:35], v[0:15]
	s_waitcnt lgkmcnt(6)
	v_mfma_f32_32x32x16_bf16 v[0:15], v[108:111], v[20:23], v[0:15]
	s_waitcnt lgkmcnt(4)
	v_mfma_f32_32x32x16_bf16 v[0:15], v[120:123], v[16:19], v[0:15]
	s_waitcnt lgkmcnt(2)
	v_mfma_f32_32x32x16_bf16 v[0:15], v[56:59], v[28:31], v[0:15]
	s_waitcnt lgkmcnt(0)
	v_mfma_f32_32x32x16_bf16 v[0:15], v[60:63], v[24:27], v[0:15]
	s_nop 11
	v_pk_mul_f32 v[0:1], v[0:1], v[44:45] op_sel_hi:[1,0]
	v_pk_mul_f32 v[2:3], v[2:3], v[44:45] op_sel_hi:[1,0]
	v_pk_mul_f32 v[4:5], v[4:5], v[44:45] op_sel_hi:[1,0]
	v_pk_mul_f32 v[6:7], v[6:7], v[44:45] op_sel_hi:[1,0]
	v_cvt_pk_bf16_f32 v0, v0, v1
	v_cvt_pk_bf16_f32 v1, v2, v3
	v_cvt_pk_bf16_f32 v2, v4, v5
	v_cvt_pk_bf16_f32 v3, v6, v7
	s_nop 1
	v_permlane32_swap_b32_e32 v0, v2
	v_permlane32_swap_b32_e32 v1, v3
	global_store_dwordx4 v[124:125], v[0:3], off offset:448
	v_pk_mul_f32 v[8:9], v[8:9], v[44:45] op_sel_hi:[1,0]
	v_pk_mul_f32 v[10:11], v[10:11], v[44:45] op_sel_hi:[1,0]
	v_pk_mul_f32 v[12:13], v[12:13], v[44:45] op_sel_hi:[1,0]
	v_pk_mul_f32 v[14:15], v[14:15], v[44:45] op_sel_hi:[1,0]
	v_cvt_pk_bf16_f32 v4, v8, v9
	v_cvt_pk_bf16_f32 v5, v10, v11
	v_cvt_pk_bf16_f32 v6, v12, v13
	v_cvt_pk_bf16_f32 v7, v14, v15
	s_nop 1
	v_permlane32_swap_b32_e32 v4, v6
	v_permlane32_swap_b32_e32 v5, v7
	global_store_dwordx4 v[124:125], v[4:7], off offset:480
	s_nop 1
	s_barrier
	s_branch .LBB0_751
